# P10+P7 as 256 balanced 160-row units, P0 prologue loads batched (silu 6-in-flight, transposer 32-in-flight)
# speedup vs baseline: 1.0236x; 1.0099x over previous
.LBB0_14:
	v_lshlrev_b32_e32 v15, 2, v0
	v_add_u32_e32 v16, 0x1000, v15
	global_load_dword v20, v15, s[62:63]
	global_load_dword v21, v15, s[62:63] offset:2048
	global_load_dword v22, v15, s[56:57]
	global_load_dword v23, v15, s[56:57] offset:2048
	global_load_dword v24, v16, s[56:57]
	global_load_dword v25, v16, s[56:57] offset:2048
	s_waitcnt vmcnt(5)
	v_mul_f32_e32 v9, 0xbfb8aa3b, v20
	v_exp_f32_e32 v9, v9
	s_nop 0
	v_add_f32_e32 v9, 1.0, v9
	v_div_scale_f32 v10, s[10:11], v9, v9, v20
	v_rcp_f32_e32 v11, v10
	v_div_scale_f32 v12, vcc, v20, v9, v20
	v_fma_f32 v13, -v10, v11, 1.0
	v_fmac_f32_e32 v11, v13, v11
	v_mul_f32_e32 v13, v12, v11
	v_fma_f32 v14, -v10, v13, v12
	v_fmac_f32_e32 v13, v14, v11
	v_fma_f32 v10, -v10, v13, v12
	v_div_fmas_f32 v10, v10, v11, v13
	v_div_fixup_f32 v2, v10, v9, v20
	ds_write_b32 v1, v2 offset:0
	s_waitcnt vmcnt(4)
	v_mul_f32_e32 v9, 0xbfb8aa3b, v21
	v_exp_f32_e32 v9, v9
	s_nop 0
	v_add_f32_e32 v9, 1.0, v9
	v_div_scale_f32 v10, s[10:11], v9, v9, v21
	v_rcp_f32_e32 v11, v10
	v_div_scale_f32 v12, vcc, v21, v9, v21
	v_fma_f32 v13, -v10, v11, 1.0
	v_fmac_f32_e32 v11, v13, v11
	v_mul_f32_e32 v13, v12, v11
	v_fma_f32 v14, -v10, v13, v12
	v_fmac_f32_e32 v13, v14, v11
	v_fma_f32 v10, -v10, v13, v12
	v_div_fmas_f32 v10, v10, v11, v13
	v_div_fixup_f32 v2, v10, v9, v21
	ds_write_b32 v1, v2 offset:2048
	s_waitcnt vmcnt(3)
	v_mul_f32_e32 v9, 0xbfb8aa3b, v22
	v_exp_f32_e32 v9, v9
	s_nop 0
	v_add_f32_e32 v9, 1.0, v9
	v_div_scale_f32 v10, s[10:11], v9, v9, v22
	v_rcp_f32_e32 v11, v10
	v_div_scale_f32 v12, vcc, v22, v9, v22
	v_fma_f32 v13, -v10, v11, 1.0
	v_fmac_f32_e32 v11, v13, v11
	v_mul_f32_e32 v13, v12, v11
	v_fma_f32 v14, -v10, v13, v12
	v_fmac_f32_e32 v13, v14, v11
	v_fma_f32 v10, -v10, v13, v12
	v_div_fmas_f32 v10, v10, v11, v13
	v_div_fixup_f32 v2, v10, v9, v22
	ds_write_b32 v1, v2 offset:4096
	s_waitcnt vmcnt(2)
	v_mul_f32_e32 v9, 0xbfb8aa3b, v23
	v_exp_f32_e32 v9, v9
	s_nop 0
	v_add_f32_e32 v9, 1.0, v9
	v_div_scale_f32 v10, s[10:11], v9, v9, v23
	v_rcp_f32_e32 v11, v10
	v_div_scale_f32 v12, vcc, v23, v9, v23
	v_fma_f32 v13, -v10, v11, 1.0
	v_fmac_f32_e32 v11, v13, v11
	v_mul_f32_e32 v13, v12, v11
	v_fma_f32 v14, -v10, v13, v12
	v_fmac_f32_e32 v13, v14, v11
	v_fma_f32 v10, -v10, v13, v12
	v_div_fmas_f32 v10, v10, v11, v13
	v_div_fixup_f32 v2, v10, v9, v23
	ds_write_b32 v1, v2 offset:6144
	s_waitcnt vmcnt(1)
	v_mul_f32_e32 v9, 0xbfb8aa3b, v24
	v_exp_f32_e32 v9, v9
	s_nop 0
	v_add_f32_e32 v9, 1.0, v9
	v_div_scale_f32 v10, s[10:11], v9, v9, v24
	v_rcp_f32_e32 v11, v10
	v_div_scale_f32 v12, vcc, v24, v9, v24
	v_fma_f32 v13, -v10, v11, 1.0
	v_fmac_f32_e32 v11, v13, v11
	v_mul_f32_e32 v13, v12, v11
	v_fma_f32 v14, -v10, v13, v12
	v_fmac_f32_e32 v13, v14, v11
	v_fma_f32 v10, -v10, v13, v12
	v_div_fmas_f32 v10, v10, v11, v13
	v_div_fixup_f32 v2, v10, v9, v24
	ds_write_b32 v1, v2 offset:8192
	s_waitcnt vmcnt(0)
	v_mul_f32_e32 v9, 0xbfb8aa3b, v25
	v_exp_f32_e32 v9, v9
	s_nop 0
	v_add_f32_e32 v9, 1.0, v9
	v_div_scale_f32 v10, s[10:11], v9, v9, v25
	v_rcp_f32_e32 v11, v10
	v_div_scale_f32 v12, vcc, v25, v9, v25
	v_fma_f32 v13, -v10, v11, 1.0
	v_fmac_f32_e32 v11, v13, v11
	v_mul_f32_e32 v13, v12, v11
	v_fma_f32 v14, -v10, v13, v12
	v_fmac_f32_e32 v13, v14, v11
	v_fma_f32 v10, -v10, v13, v12
	v_div_fmas_f32 v10, v10, v11, v13
	v_div_fixup_f32 v2, v10, v9, v25
	ds_write_b32 v1, v2 offset:10240
	s_or_b64 exec, exec, s[0:1]
	s_add_u32 s4, s28, 0x100000
	s_mul_i32 s0, s33, 0x300
	s_addc_u32 s5, s29, 0
	s_add_i32 s0, s0, 0
	v_lshlrev_b32_e32 v2, 2, v164
	s_mul_hi_u32 s1, s6, 0x9000
	s_mul_i32 s6, s6, 0x9000
	v_add_u32_e32 v1, s0, v2
	s_movk_i32 s0, 0xc0
	v_lshrrev_b32_e32 v3, 6, v0
	v_cmp_gt_u32_e32 vcc, s0, v0
	v_lshlrev_b32_e32 v7, 8, v3
	v_mul_u32_u24_e32 v3, 0x2400, v3
	s_add_u32 s0, s64, s6
	v_add_u32_e32 v6, 0, v2
	v_or_b32_e32 v10, v3, v164
	v_mov_b32_e32 v3, 0
	s_addc_u32 s1, s65, s1
	s_mov_b32 s12, 0x9000
	v_lshl_add_u64 v[4:5], s[0:1], 0, v[2:3]
	s_lshl_b32 s6, s2, 6
	s_lshl_b32 s13, s3, 6
	s_mov_b32 s14, 0x12000
	s_mov_b32 s15, 0x1b000
	s_mov_b32 s19, 0x24000
	s_mov_b32 s20, 0x2d000
	s_mov_b32 s21, 0x36000
	s_mov_b32 s22, 0x3f000
	s_mov_b32 s23, 0x48000
	s_mov_b32 s24, 0x51000
	s_mov_b32 s25, 0x5a000
	s_mov_b32 s26, 0x63000
	s_mov_b32 s27, 0x6c000
	s_mov_b32 s56, 0x75000
	s_mov_b32 s57, 0x7e000
	s_mov_b32 s62, 0x87000
	v_add_u32_e32 v11, v6, v7
	s_mov_b32 s63, s2
	s_waitcnt lgkmcnt(0)
	s_barrier
	s_branch .LBB0_17

.LBB0_32:
	v_lshl_add_u64 v[40:41], v[22:23], 0, s[6:7]
	v_lshl_add_u64 v[42:43], v[20:21], 0, s[6:7]
	v_lshl_add_u64 v[44:45], v[18:19], 0, s[6:7]
	v_lshl_add_u64 v[46:47], v[16:17], 0, s[6:7]
	v_lshl_add_u64 v[48:49], v[14:15], 0, s[6:7]
	v_lshl_add_u64 v[50:51], v[12:13], 0, s[6:7]
	v_lshl_add_u64 v[52:53], v[10:11], 0, s[6:7]
	v_lshl_add_u64 v[54:55], v[8:9], 0, s[6:7]
	global_load_dword v60, v[40:41], off nt
	global_load_dword v61, v[42:43], off nt
	global_load_dword v62, v[44:45], off nt
	global_load_dword v63, v[46:47], off nt
	global_load_dword v64, v[48:49], off nt
	global_load_dword v65, v[50:51], off nt
	global_load_dword v66, v[52:53], off nt
	global_load_dword v67, v[54:55], off nt
	s_add_u32 s6, s6, 0x58000
	s_addc_u32 s7, s7, 0
	v_lshl_add_u64 v[40:41], v[22:23], 0, s[6:7]
	v_lshl_add_u64 v[42:43], v[20:21], 0, s[6:7]
	v_lshl_add_u64 v[44:45], v[18:19], 0, s[6:7]
	v_lshl_add_u64 v[46:47], v[16:17], 0, s[6:7]
	v_lshl_add_u64 v[48:49], v[14:15], 0, s[6:7]
	v_lshl_add_u64 v[50:51], v[12:13], 0, s[6:7]
	v_lshl_add_u64 v[52:53], v[10:11], 0, s[6:7]
	v_lshl_add_u64 v[54:55], v[8:9], 0, s[6:7]
	global_load_dword v68, v[40:41], off nt
	global_load_dword v69, v[42:43], off nt
	global_load_dword v70, v[44:45], off nt
	global_load_dword v71, v[46:47], off nt
	global_load_dword v72, v[48:49], off nt
	global_load_dword v73, v[50:51], off nt
	global_load_dword v74, v[52:53], off nt
	global_load_dword v75, v[54:55], off nt
	s_add_u32 s6, s6, 0x58000
	s_addc_u32 s7, s7, 0
	v_lshl_add_u64 v[40:41], v[22:23], 0, s[6:7]
	v_lshl_add_u64 v[42:43], v[20:21], 0, s[6:7]
	v_lshl_add_u64 v[44:45], v[18:19], 0, s[6:7]
	v_lshl_add_u64 v[46:47], v[16:17], 0, s[6:7]
	v_lshl_add_u64 v[48:49], v[14:15], 0, s[6:7]
	v_lshl_add_u64 v[50:51], v[12:13], 0, s[6:7]
	v_lshl_add_u64 v[52:53], v[10:11], 0, s[6:7]
	v_lshl_add_u64 v[54:55], v[8:9], 0, s[6:7]
	global_load_dword v76, v[40:41], off nt
	global_load_dword v77, v[42:43], off nt
	global_load_dword v78, v[44:45], off nt
	global_load_dword v79, v[46:47], off nt
	global_load_dword v80, v[48:49], off nt
	global_load_dword v81, v[50:51], off nt
	global_load_dword v82, v[52:53], off nt
	global_load_dword v83, v[54:55], off nt
	s_add_u32 s6, s6, 0x58000
	s_addc_u32 s7, s7, 0
	v_lshl_add_u64 v[40:41], v[22:23], 0, s[6:7]
	v_lshl_add_u64 v[42:43], v[20:21], 0, s[6:7]
	v_lshl_add_u64 v[44:45], v[18:19], 0, s[6:7]
	v_lshl_add_u64 v[46:47], v[16:17], 0, s[6:7]
	v_lshl_add_u64 v[48:49], v[14:15], 0, s[6:7]
	v_lshl_add_u64 v[50:51], v[12:13], 0, s[6:7]
	v_lshl_add_u64 v[52:53], v[10:11], 0, s[6:7]
	v_lshl_add_u64 v[54:55], v[8:9], 0, s[6:7]
	global_load_dword v84, v[40:41], off nt
	global_load_dword v85, v[42:43], off nt
	global_load_dword v86, v[44:45], off nt
	global_load_dword v87, v[46:47], off nt
	global_load_dword v88, v[48:49], off nt
	global_load_dword v89, v[50:51], off nt
	global_load_dword v90, v[52:53], off nt
	global_load_dword v91, v[54:55], off nt
	v_add_u32_e32 v92, 0x400, v39
	v_add_u32_e32 v93, 0x840, v39
	v_add_u32_e32 v94, 0xc40, v39
	v_add_u32_e32 v95, 0x1080, v39
	v_add_u32_e32 v96, 0x1480, v39
	v_add_u32_e32 v97, 0x18c0, v39
	v_add_u32_e32 v98, 0x1cc0, v39
	s_waitcnt vmcnt(30)
	ds_write2_b32 v39, v60, v61 offset1:66
	s_waitcnt vmcnt(28)
	ds_write2_b32 v39, v62, v63 offset0:132 offset1:198
	s_waitcnt vmcnt(26)
	ds_write2_b32 v92, v64, v65 offset0:8 offset1:74
	s_waitcnt vmcnt(24)
	ds_write2_b32 v92, v66, v67 offset0:140 offset1:206
	s_waitcnt vmcnt(22)
	ds_write2_b32 v93, v68, v69 offset1:66
	s_waitcnt vmcnt(20)
	ds_write2_b32 v93, v70, v71 offset0:132 offset1:198
	s_waitcnt vmcnt(18)
	ds_write2_b32 v94, v72, v73 offset0:8 offset1:74
	s_waitcnt vmcnt(16)
	ds_write2_b32 v94, v74, v75 offset0:140 offset1:206
	s_waitcnt vmcnt(14)
	ds_write2_b32 v95, v76, v77 offset1:66
	s_waitcnt vmcnt(12)
	ds_write2_b32 v95, v78, v79 offset0:132 offset1:198
	s_waitcnt vmcnt(10)
	ds_write2_b32 v96, v80, v81 offset0:8 offset1:74
	s_waitcnt vmcnt(8)
	ds_write2_b32 v96, v82, v83 offset0:140 offset1:206
	s_waitcnt vmcnt(6)
	ds_write2_b32 v97, v84, v85 offset1:66
	s_waitcnt vmcnt(4)
	ds_write2_b32 v97, v86, v87 offset0:132 offset1:198
	s_waitcnt vmcnt(2)
	ds_write2_b32 v98, v88, v89 offset0:8 offset1:74
	s_waitcnt vmcnt(0)
	ds_write2_b32 v98, v90, v91 offset0:140 offset1:206
	s_waitcnt lgkmcnt(0)
	ds_read2_b32 v[12:13], v7 offset0:33 offset1:41
	ds_read2_b32 v[14:15], v7 offset1:8
	ds_read2_b32 v[16:17], v7 offset0:66 offset1:74
	ds_read2_b32 v[18:19], v7 offset0:99 offset1:107
	ds_read2_b32 v[20:21], v7 offset0:132 offset1:140
	ds_read2_b32 v[22:23], v7 offset0:165 offset1:173
	ds_read2_b32 v[40:41], v7 offset0:198 offset1:206
	ds_read2_b32 v[42:43], v7 offset0:231 offset1:239
	s_waitcnt lgkmcnt(6)
	v_cvt_pk_bf16_f32 v8, v14, v12
	v_or_b32_e32 v12, s0, v1
	v_cmp_lt_i32_e32 vcc, s11, v12
	s_waitcnt lgkmcnt(4)
	v_cvt_pk_bf16_f32 v9, v16, v18
	v_bitop3_b32 v18, s0, v38, v1 bitop3:0xc8
	v_cndmask_b32_e32 v14, 0, v36, vcc
	v_add_lshl_u32 v14, v14, v12, 1
	v_lshlrev_b32_e32 v12, 2, v12
	v_and_b32_e32 v14, 0xffffff00, v14
	v_cndmask_b32_e32 v16, 0, v37, vcc
	v_and_or_b32 v12, v12, 16, v18
	v_or3_b32 v46, v12, v16, v14
	v_ashrrev_i32_e32 v47, 31, v46
	v_lshl_add_u64 v[44:45], s[4:5], 1, v[2:3]
	v_lshlrev_b64 v[46:47], 11, v[46:47]
	v_or_b32_e32 v12, s0, v24
	s_waitcnt lgkmcnt(2)
	v_cvt_pk_bf16_f32 v10, v20, v22
	s_waitcnt lgkmcnt(0)
	v_cvt_pk_bf16_f32 v11, v40, v42
	v_lshl_add_u64 v[46:47], v[44:45], 0, v[46:47]
	v_cmp_lt_i32_e32 vcc, s11, v12
	global_store_dwordx4 v[46:47], v[8:11], off
	s_add_i32 s10, s10, s12
	v_cndmask_b32_e32 v14, 0, v37, vcc
	v_cvt_pk_bf16_f32 v8, v15, v13
	v_cndmask_b32_e32 v13, 0, v36, vcc
	v_add_lshl_u32 v13, v13, v12, 1
	v_lshlrev_b32_e32 v12, 2, v12
	v_and_b32_e32 v12, 16, v12
	v_bitop3_b32 v15, s0, v38, v24 bitop3:0xc8
	v_and_b32_e32 v13, 0xffffff00, v13
	v_or3_b32 v12, v15, v12, v14
	v_or3_b32 v12, v12, v13, 4
	v_ashrrev_i32_e32 v13, 31, v12
	v_lshlrev_b64 v[12:13], 11, v[12:13]
	v_cvt_pk_bf16_f32 v9, v17, v19
	v_cvt_pk_bf16_f32 v10, v21, v23
	v_cvt_pk_bf16_f32 v11, v41, v43
	v_lshl_add_u64 v[12:13], v[44:45], 0, v[12:13]
	ds_read2_b32 v[14:15], v7 offset0:16 offset1:24
	ds_read2_b32 v[16:17], v7 offset0:49 offset1:57
	ds_read2_b32 v[18:19], v7 offset0:82 offset1:90
	ds_read2_b32 v[20:21], v7 offset0:115 offset1:123
	ds_read2_b32 v[22:23], v7 offset0:148 offset1:156
	ds_read2_b32 v[40:41], v7 offset0:181 offset1:189
	ds_read2_b32 v[42:43], v7 offset0:214 offset1:222
	ds_read2_b32 v[46:47], v7 offset0:247 offset1:255
	global_store_dwordx4 v[12:13], v[8:11], off
	v_or_b32_e32 v12, s0, v25
	v_cmp_lt_i32_e32 vcc, s11, v12
	s_waitcnt lgkmcnt(6)
	v_cvt_pk_bf16_f32 v8, v14, v16
	v_bitop3_b32 v16, s0, v38, v25 bitop3:0xc8
	v_cndmask_b32_e32 v13, 0, v36, vcc
	v_add_lshl_u32 v13, v13, v12, 1
	v_lshlrev_b32_e32 v12, 2, v12
	v_cndmask_b32_e32 v14, 0, v37, vcc
	v_and_b32_e32 v12, 16, v12
	v_and_b32_e32 v13, 0xffffff00, v13
	v_or3_b32 v12, v16, v12, v14
	v_or3_b32 v12, v12, v13, 8
	v_ashrrev_i32_e32 v13, 31, v12
	v_lshlrev_b64 v[12:13], 11, v[12:13]
	s_waitcnt lgkmcnt(4)
	v_cvt_pk_bf16_f32 v9, v18, v20
	s_waitcnt lgkmcnt(2)
	v_cvt_pk_bf16_f32 v10, v22, v40
	s_waitcnt lgkmcnt(0)
	v_cvt_pk_bf16_f32 v11, v42, v46
	v_lshl_add_u64 v[12:13], v[44:45], 0, v[12:13]
	global_store_dwordx4 v[12:13], v[8:11], off
	s_cmpk_lt_i32 s10, 0xb00
	s_nop 0
	v_or_b32_e32 v8, s0, v26
	v_cmp_lt_i32_e32 vcc, s11, v8
	v_bitop3_b32 v11, s0, v38, v26 bitop3:0xc8
	s_nop 0
	v_cndmask_b32_e32 v9, 0, v36, vcc
	v_add_lshl_u32 v9, v9, v8, 1
	v_lshlrev_b32_e32 v8, 2, v8
	v_cndmask_b32_e32 v10, 0, v37, vcc
	v_and_b32_e32 v8, 16, v8
	v_and_b32_e32 v9, 0xffffff00, v9
	v_or3_b32 v8, v11, v8, v10
	v_or3_b32 v12, v8, v9, 12
	v_ashrrev_i32_e32 v13, 31, v12
	v_lshlrev_b64 v[12:13], 11, v[12:13]
	v_cvt_pk_bf16_f32 v8, v15, v17
	v_cvt_pk_bf16_f32 v9, v19, v21
	v_cvt_pk_bf16_f32 v10, v23, v41
	v_cvt_pk_bf16_f32 v11, v43, v47
	v_lshl_add_u64 v[12:13], v[44:45], 0, v[12:13]
	global_store_dwordx4 v[12:13], v[8:11], off
	s_waitcnt lgkmcnt(0)
	s_cbranch_scc1 .LBB0_31

.LBB0_824:
	s_cmp_lt_i32 s30, 8
	s_cselect_b64 s[4:5], -1, 0
	s_and_b64 s[4:5], s[4:5], s[0:1]
	s_andn2_b64 vcc, exec, s[4:5]
	s_cbranch_vccnz .LBB0_841
	s_cmpk_gt_i32 s2, 0xff
	v_readfirstlane_b32 s1, v0
	s_cbranch_scc1 .LBB0_841
	s_add_u32 s26, s28, 0xc300000
	s_addc_u32 s27, s29, 0
	v_lshlrev_b32_e32 v1, 4, v0
	s_add_u32 s56, s28, 0x2900000
	v_and_b32_e32 v2, 32, v0
	v_or_b32_e32 v13, 0x2000, v1
	s_addc_u32 s57, s29, 0
	v_bfe_u32 v12, v0, 2, 4
	v_bitop3_b32 v10, v1, v2, 48 bitop3:0x6c
	v_lshrrev_b32_e32 v1, 7, v13
	s_movk_i32 s0, 0x70
	s_ashr_i32 s59, s2, 31
	v_and_or_b32 v1, v1, s0, v12
	s_lshr_b32 s0, s59, 29
	s_add_i32 s0, s2, s0
	s_lshr_b32 s10, s1, 6
	s_ashr_i32 s6, s0, 3
	s_and_b32 s0, s0, -8
	s_lshr_b32 s12, s1, 8
	s_lshl_b32 s58, s10, 10
	s_sub_i32 s0, s2, s0
	s_cmp_lt_i32 s0, 0
	s_cselect_b32 s7, 33, 32
	s_mul_i32 s0, s0, s7
	s_add_i32 s0, s0, s6
	s_ashr_i32 s6, s0, 31
	s_lshr_b32 s6, s6, 27
	s_add_i32 s6, s0, s6
	s_ashr_i32 s7, s6, 5
	s_andn2_b32 s6, s6, 31
	s_sub_i32 s6, s0, s6
	s_bfe_i32 s0, s6, 0x80000
	s_bfe_u32 s0, s0, 0x3000c
	s_add_i32 s8, s6, s0
	s_bfe_i32 s0, s8, 0x80000
	s_and_b32 s8, s8, 0xf8
	s_sub_i32 s6, s6, s8
	s_lshl_b32 s7, s7, 3
	s_sext_i32_i16 s0, s0
	s_sext_i32_i8 s6, s6
	s_lshr_b32 s0, s0, 3
	s_add_i32 s24, s7, s6
	s_ashr_i32 s25, s24, 31
	s_bfe_i64 s[8:9], s[0:1], 0x100000
	s_mul_i32 s6, s24, 0x50000
	s_mul_hi_i32 s7, s24, 0x50000
	s_lshl_b64 s[8:9], s[8:9], 19
	v_and_b32_e32 v11, 64, v0
	v_lshrrev_b32_e32 v3, 3, v0
	s_add_u32 s52, s56, s8
	v_or_b32_e32 v2, v10, v11
	v_and_or_b32 v3, v3, 48, v12
	s_addc_u32 s53, s57, s9
	s_add_i32 s25, s58, 0
	v_lshl_or_b32 v130, v3, 11, v2
	s_add_i32 m0, s25, 0x10000
	v_lshl_or_b32 v132, v1, 11, v2
	global_load_lds_dwordx4 v130, s[52:53]
	s_add_i32 m0, s25, 0x12000
	s_add_u32 s8, s52, 0x40000
	global_load_lds_dwordx4 v132, s[52:53]
	s_addc_u32 s9, s53, 0
	s_add_i32 m0, s25, 0x14000
	v_mov_b32_e32 v131, 0
	global_load_lds_dwordx4 v130, s[8:9]
	s_add_i32 m0, s25, 0x16000
	s_add_u32 s50, s26, s6
	s_addc_u32 s51, s27, s7
	s_sub_u32 s50, s50, 0x18000
	s_subb_u32 s51, s51, 0
	s_add_i32 s60, s25, 0x2000
	global_load_lds_dwordx4 v132, s[8:9]
	s_mov_b32 m0, s25
	s_add_u32 s6, s50, 0x28000
	global_load_lds_dwordx4 v130, s[50:51]
	s_mov_b32 m0, s60
	s_addc_u32 s7, s51, 0
	s_add_i32 s61, s25, 0x4000
	global_load_lds_dwordx4 v132, s[50:51]
	s_mov_b32 m0, s61
	s_add_i32 s62, s25, 0x6000
	global_load_lds_dwordx4 v130, s[6:7]
	s_mov_b32 m0, s62
	v_mov_b32_e32 v133, v131
	global_load_lds_dwordx4 v132, s[6:7]
	s_cmp_eq_u32 s12, 1
	s_mov_b32 s63, 0
	v_lshl_add_u64 v[8:9], s[52:53], 0, v[130:131]
	v_lshl_add_u64 v[6:7], s[52:53], 0, v[132:133]
	s_mov_b64 s[6:7], 0x40000
	v_lshl_add_u64 v[2:3], s[50:51], 0, v[130:131]
	s_cselect_b64 s[8:9], -1, 0
	s_cmp_lg_u32 s12, 1
	v_lshl_add_u64 v[4:5], s[50:51], 0, v[132:133]
	s_cbranch_scc1 .LBB0_828
	s_barrier
.LBB0_828:
	s_lshl_b32 s10, s10, 5
	s_and_b32 s18, s10, 0x60
	s_mov_b64 s[10:11], 0x80
	s_add_i32 m0, s25, 0x18000
	v_lshl_add_u64 v[8:9], v[8:9], 0, s[10:11]
	s_ashr_i32 s64, s3, 31
	s_lshl_b32 s13, s12, 13
	s_lshl_b32 s19, s18, 7
	s_waitcnt vmcnt(2)
	s_barrier
	global_load_lds_dwordx4 v[8:9], off
	v_lshl_add_u64 v[6:7], v[6:7], 0, s[10:11]
	s_add_i32 m0, s25, 0x1a000
	s_add_i32 s65, s25, 0x8000
	s_add_i32 s66, s25, 0xa000
	global_load_lds_dwordx4 v[6:7], off
	v_lshl_add_u64 v[2:3], v[2:3], 0, s[10:11]
	s_mov_b32 m0, s65
	s_add_u32 s14, s52, 0x40080
	global_load_lds_dwordx4 v[2:3], off
	v_lshl_add_u64 v[2:3], v[4:5], 0, s[10:11]
	s_mov_b32 m0, s66
	s_addc_u32 s15, s53, 0
	global_load_lds_dwordx4 v[2:3], off
	s_add_i32 m0, s25, 0x1c000
	v_lshl_add_u64 v[2:3], s[14:15], 0, v[130:131]
	global_load_lds_dwordx4 v[2:3], off
	v_lshl_add_u64 v[2:3], s[14:15], 0, v[132:133]
	s_add_i32 m0, s25, 0x1e000
	v_lshrrev_b32_e32 v1, 1, v0
	global_load_lds_dwordx4 v[2:3], off
	v_and_b32_e32 v3, 24, v1
	s_sext_i32_i8 s73, s0
	v_lshlrev_b32_e32 v4, 1, v3
	v_lshlrev_b32_e32 v1, 6, v0
	s_movk_i32 s0, 0x3c0
	v_and_b32_e32 v2, 15, v0
	v_and_or_b32 v5, v1, s0, v4
	v_lshlrev_b32_e32 v1, 2, v0
	v_or_b32_e32 v143, s18, v3
	v_lshlrev_b32_e32 v3, 8, v0
	v_and_b32_e32 v6, 32, v1
	v_mad_u32_u24 v1, s12, 48, v2
	v_lshl_or_b32 v2, v2, 6, v4
	v_and_b32_e32 v3, 0x18000, v3
	v_lshlrev_b32_e32 v4, 11, v12
	v_or3_b32 v3, v10, v3, v4
	v_add_u32_e32 v134, v3, v11
	v_lshlrev_b32_e32 v3, 4, v13
	s_waitcnt vmcnt(6)
	s_cmpk_lt_u32 s1, 0x100
	v_and_b32_e32 v3, 0x38000, v3
	v_bitop3_b32 v2, v2, s13, v6 bitop3:0xde
	v_bitop3_b32 v142, s19, v5, v6 bitop3:0xf6
	s_cselect_b64 s[12:13], -1, 0
	v_or3_b32 v3, v10, v3, v4
	s_add_i32 s67, 0, 0x10000
	s_add_i32 s68, 0, 0x14000
	v_mov_b32_e32 v135, v131
	v_add_u32_e32 v136, v3, v11
	v_mov_b32_e32 v137, v131
	v_mov_b64_e32 v[138:139], 0x100
	v_mov_b64_e32 v[140:141], 0xff
	v_add_u32_e32 v144, s67, v142
	v_add_u32_e32 v145, s68, v142
	s_movk_i32 s98, 0x1000
	s_cmp_lg_u32 s12, 0
	s_cselect_b32 s98, 0x1800, s98
	v_add_u32_e32 v146, s98, v2
	s_mov_b32 s69, 0x40000
	s_mov_b64 s[14:15], 0x48000
	s_mov_b32 s70, 0x48000
	s_mov_b64 s[18:19], 0x50000
	s_mov_b32 s71, 0x50000
	s_mov_b64 s[20:21], 0x58000
	s_mov_b32 s72, 0x58000
	s_barrier
	s_waitcnt vmcnt(0)
	s_branch .LBB0_831

.LBB0_831:
	s_add_i32 s63, s63, 1
	s_mul_i32 s0, s63, s64
	s_mul_hi_u32 s1, s63, s3
	s_add_i32 s1, s1, s0
	s_mul_i32 s0, s63, s3
	s_add_u32 s46, s0, s2
	s_addc_u32 s47, s1, s59
	v_cmp_gt_i64_e32 vcc, s[46:47], v[140:141]
	v_cmp_lt_i64_e64 s[0:1], s[46:47], v[138:139]
	s_cbranch_vccnz .LBB0_833
	s_ashr_i32 s22, s46, 31
	s_lshr_b32 s22, s22, 29
	s_add_i32 s22, s46, s22
	s_ashr_i32 s23, s22, 3
	s_and_b32 s22, s22, -8
	s_sub_i32 s22, s46, s22
	s_cmp_lt_i32 s22, 0
	s_cselect_b32 s44, 33, 32
	s_mul_i32 s22, s22, s44
	s_add_i32 s22, s22, s23
	s_ashr_i32 s23, s22, 31
	s_lshr_b32 s23, s23, 27
	s_add_i32 s23, s22, s23
	s_ashr_i32 s44, s23, 5
	s_lshl_b32 s44, s44, 3
	s_sub_i32 s45, 64, s44
	s_min_i32 s45, s45, 8
	s_abs_i32 s46, s45
	v_cvt_f32_u32_e32 v2, s46
	s_sub_i32 s48, 0, s46
	s_andn2_b32 s23, s23, 31
	s_sub_i32 s23, s22, s23
	v_rcp_iflag_f32_e32 v2, v2
	s_abs_i32 s22, s23
	s_xor_b32 s47, s23, s45
	s_ashr_i32 s47, s47, 31
	v_mul_f32_e32 v2, 0x4f7ffffe, v2
	v_cvt_u32_f32_e32 v2, v2
	s_nop 0
	v_readfirstlane_b32 s49, v2
	s_mul_i32 s48, s48, s49
	s_mul_hi_u32 s48, s49, s48
	s_add_i32 s49, s49, s48
	s_mul_hi_u32 s48, s22, s49
	s_mul_i32 s49, s48, s46
	s_sub_i32 s22, s22, s49
	s_add_i32 s54, s48, 1
	s_sub_i32 s49, s22, s46
	s_cmp_ge_u32 s22, s46
	s_cselect_b32 s48, s54, s48
	s_cselect_b32 s22, s49, s22
	s_add_i32 s49, s48, 1
	s_cmp_ge_u32 s22, s46
	s_cselect_b32 s22, s49, s48
	s_xor_b32 s22, s22, s47
	s_sub_i32 s22, s22, s47
	s_mul_i32 s45, s22, s45
	s_sub_i32 s23, s23, s45
	s_add_i32 s44, s44, s23
.LBB0_833:
	s_ashr_i32 s45, s44, 31
	s_mul_hi_i32 s47, s44, 0x50000
	s_mul_i32 s46, s44, 0x50000
	s_add_u32 s46, s26, s46
	s_addc_u32 s47, s27, s47
	s_sub_u32 s46, s46, 0x18000
	s_subb_u32 s47, s47, 0
	s_and_b64 s[48:49], s[0:1], exec
	s_cselect_b32 s45, s47, s51
	s_cselect_b32 s74, s46, s50
	s_ashr_i32 s23, s22, 31
	s_lshl_b64 s[48:49], s[22:23], 19
	s_add_u32 s48, s56, s48
	s_addc_u32 s49, s57, s49
	s_and_b64 s[54:55], s[0:1], exec
	s_cselect_b32 s23, s49, s53
	s_cselect_b32 s75, s48, s52
	s_add_u32 s50, s50, 0x28080
	s_addc_u32 s51, s51, 0
	s_add_u32 s76, s52, 0x100
	v_mov_b32_e32 v2, 0
	s_addc_u32 s77, s53, 0
	s_mov_b32 s78, -2
	v_mov_b32_e32 v3, v2
	v_mov_b32_e32 v4, v2
	v_mov_b32_e32 v5, v2
	v_mov_b32_e32 v6, v2
	v_mov_b32_e32 v7, v2
	v_mov_b32_e32 v8, v2
	v_mov_b32_e32 v9, v2
	v_mov_b32_e32 v10, v2
	v_mov_b32_e32 v11, v2
	v_mov_b32_e32 v12, v2
	v_mov_b32_e32 v13, v2
	v_mov_b32_e32 v14, v2
	v_mov_b32_e32 v15, v2
	v_mov_b32_e32 v16, v2
	v_mov_b32_e32 v17, v2
	v_mov_b32_e32 v26, v2
	v_mov_b32_e32 v27, v2
	v_mov_b32_e32 v28, v2
	v_mov_b32_e32 v29, v2
	v_mov_b32_e32 v30, v2
	v_mov_b32_e32 v31, v2
	v_mov_b32_e32 v32, v2
	v_mov_b32_e32 v33, v2
	v_mov_b32_e32 v42, v2
	v_mov_b32_e32 v43, v2
	v_mov_b32_e32 v44, v2
	v_mov_b32_e32 v45, v2
	v_mov_b32_e32 v46, v2
	v_mov_b32_e32 v47, v2
	v_mov_b32_e32 v48, v2
	v_mov_b32_e32 v49, v2
	v_mov_b32_e32 v18, v2
	v_mov_b32_e32 v19, v2
	v_mov_b32_e32 v20, v2
	v_mov_b32_e32 v21, v2
	v_mov_b32_e32 v22, v2
	v_mov_b32_e32 v23, v2
	v_mov_b32_e32 v24, v2
	v_mov_b32_e32 v25, v2
	v_mov_b32_e32 v34, v2
	v_mov_b32_e32 v35, v2
	v_mov_b32_e32 v36, v2
	v_mov_b32_e32 v37, v2
	v_mov_b32_e32 v38, v2
	v_mov_b32_e32 v39, v2
	v_mov_b32_e32 v40, v2
	v_mov_b32_e32 v41, v2
	v_mov_b32_e32 v50, v2
	v_mov_b32_e32 v51, v2
	v_mov_b32_e32 v52, v2
	v_mov_b32_e32 v53, v2
	v_mov_b32_e32 v54, v2
	v_mov_b32_e32 v55, v2
	v_mov_b32_e32 v56, v2
	v_mov_b32_e32 v57, v2
	v_mov_b32_e32 v58, v2
	v_mov_b32_e32 v59, v2
	v_mov_b32_e32 v60, v2
	v_mov_b32_e32 v61, v2
	v_mov_b32_e32 v62, v2
	v_mov_b32_e32 v63, v2
	v_mov_b32_e32 v64, v2
	v_mov_b32_e32 v65, v2
	v_mov_b32_e32 v66, v2
	v_mov_b32_e32 v67, v2
	v_mov_b32_e32 v68, v2
	v_mov_b32_e32 v69, v2
	v_mov_b32_e32 v70, v2
	v_mov_b32_e32 v71, v2
	v_mov_b32_e32 v72, v2
	v_mov_b32_e32 v73, v2
	v_mov_b32_e32 v74, v2
	v_mov_b32_e32 v75, v2
	v_mov_b32_e32 v76, v2
	v_mov_b32_e32 v77, v2
	v_mov_b32_e32 v78, v2
	v_mov_b32_e32 v79, v2
	v_mov_b32_e32 v80, v2
	v_mov_b32_e32 v81, v2
	v_mov_b32_e32 v90, v2
	v_mov_b32_e32 v91, v2
	v_mov_b32_e32 v92, v2
	v_mov_b32_e32 v93, v2
	v_mov_b32_e32 v94, v2
	v_mov_b32_e32 v95, v2
	v_mov_b32_e32 v96, v2
	v_mov_b32_e32 v97, v2
	v_mov_b32_e32 v106, v2
	v_mov_b32_e32 v107, v2
	v_mov_b32_e32 v108, v2
	v_mov_b32_e32 v109, v2
	v_mov_b32_e32 v110, v2
	v_mov_b32_e32 v111, v2
	v_mov_b32_e32 v112, v2
	v_mov_b32_e32 v113, v2
	v_mov_b32_e32 v82, v2
	v_mov_b32_e32 v83, v2
	v_mov_b32_e32 v84, v2
	v_mov_b32_e32 v85, v2
	v_mov_b32_e32 v86, v2
	v_mov_b32_e32 v87, v2
	v_mov_b32_e32 v88, v2
	v_mov_b32_e32 v89, v2
	v_mov_b32_e32 v98, v2
	v_mov_b32_e32 v99, v2
	v_mov_b32_e32 v100, v2
	v_mov_b32_e32 v101, v2
	v_mov_b32_e32 v102, v2
	v_mov_b32_e32 v103, v2
	v_mov_b32_e32 v104, v2
	v_mov_b32_e32 v105, v2
	v_mov_b32_e32 v114, v2
	v_mov_b32_e32 v115, v2
	v_mov_b32_e32 v116, v2
	v_mov_b32_e32 v117, v2
	v_mov_b32_e32 v118, v2
	v_mov_b32_e32 v119, v2
	v_mov_b32_e32 v120, v2
	v_mov_b32_e32 v121, v2
	v_mov_b32_e32 v122, v2
	v_mov_b32_e32 v123, v2
	v_mov_b32_e32 v124, v2
	v_mov_b32_e32 v125, v2
	v_mov_b32_e32 v126, v2
	v_mov_b32_e32 v127, v2
	v_mov_b32_e32 v128, v2
	v_mov_b32_e32 v129, v2
.LBB0_834:
	s_cmp_lt_u32 s58, 0x1800
	s_cbranch_scc1 .Lp7_loopA
.Lp7_loopB:
	ds_read_b128 v[148:151], v144
	ds_read_b128 v[152:155], v144 offset:1024
	ds_read_b128 v[156:159], v144 offset:2048
	ds_read_b128 v[160:163], v144 offset:3072
	ds_read_b128 v[166:169], v145
	ds_read_b128 v[170:173], v145 offset:1024
	ds_read_b128 v[174:177], v145 offset:2048
	ds_read_b128 v[178:181], v145 offset:3072
	s_add_u32 s52, s50, 0xfffd8080
	s_addc_u32 s53, s51, -1
	s_cmp_eq_u32 s78, 12
	s_cselect_b32 s55, s45, s53
	s_cselect_b32 s54, s74, s52
	s_cselect_b32 s53, s23, s77
	s_cselect_b32 s52, s75, s76
	v_lshl_add_u64 v[214:215], s[50:51], 0, v[134:135]
	s_add_i32 m0, s25, 0xc000
	ds_read_b128 v[182:185], v146
	ds_read_b128 v[186:189], v146 offset:1024
	ds_read_b128 v[190:193], v146 offset:2048
	ds_read_b128 v[194:197], v146 offset:3072
	ds_read_b128 v[198:201], v146 offset:4096
	ds_read_b128 v[202:205], v146 offset:5120
	global_load_lds_dwordx4 v[214:215], off
	v_lshl_add_u64 v[214:215], s[50:51], 0, v[136:137]
	s_add_i32 m0, s25, 0xe000
	s_nop 0
	global_load_lds_dwordx4 v[214:215], off
	s_waitcnt vmcnt(8)
	s_waitcnt lgkmcnt(0)
	s_barrier
	s_setprio 1
	s_waitcnt lgkmcnt(0)
	v_mfma_f32_16x16x32_bf16 v[126:129], v[148:151], v[182:185], v[126:129]
	v_mfma_f32_16x16x32_bf16 v[122:125], v[156:159], v[182:185], v[122:125]
	v_mfma_f32_16x16x32_bf16 v[126:129], v[152:155], v[186:189], v[126:129]
	v_mfma_f32_16x16x32_bf16 v[122:125], v[160:163], v[186:189], v[122:125]
	v_mfma_f32_16x16x32_bf16 v[110:113], v[166:169], v[182:185], v[110:113]
	v_mfma_f32_16x16x32_bf16 v[106:109], v[174:177], v[182:185], v[106:109]
	v_mfma_f32_16x16x32_bf16 v[110:113], v[170:173], v[186:189], v[110:113]
	v_mfma_f32_16x16x32_bf16 v[106:109], v[178:181], v[186:189], v[106:109]
	v_mfma_f32_16x16x32_bf16 v[118:121], v[148:151], v[190:193], v[118:121]
	v_mfma_f32_16x16x32_bf16 v[114:117], v[156:159], v[190:193], v[114:117]
	v_mfma_f32_16x16x32_bf16 v[118:121], v[152:155], v[194:197], v[118:121]
	v_mfma_f32_16x16x32_bf16 v[114:117], v[160:163], v[194:197], v[114:117]
	v_mfma_f32_16x16x32_bf16 v[94:97], v[166:169], v[190:193], v[94:97]
	v_mfma_f32_16x16x32_bf16 v[90:93], v[174:177], v[190:193], v[90:93]
	v_mfma_f32_16x16x32_bf16 v[94:97], v[170:173], v[194:197], v[94:97]
	v_mfma_f32_16x16x32_bf16 v[90:93], v[178:181], v[194:197], v[90:93]
	s_cmp_eq_u32 s12, 0
	s_cbranch_scc1 .Lp7_sk0
	v_mfma_f32_16x16x32_bf16 v[102:105], v[148:151], v[198:201], v[102:105]
	v_mfma_f32_16x16x32_bf16 v[98:101], v[156:159], v[198:201], v[98:101]
	v_mfma_f32_16x16x32_bf16 v[102:105], v[152:155], v[202:205], v[102:105]
	v_mfma_f32_16x16x32_bf16 v[98:101], v[160:163], v[202:205], v[98:101]
	v_mfma_f32_16x16x32_bf16 v[78:81], v[166:169], v[198:201], v[78:81]
	v_mfma_f32_16x16x32_bf16 v[74:77], v[174:177], v[198:201], v[74:77]
	v_mfma_f32_16x16x32_bf16 v[78:81], v[170:173], v[202:205], v[78:81]
	v_mfma_f32_16x16x32_bf16 v[74:77], v[178:181], v[202:205], v[74:77]
.Lp7_sk0:
	s_setprio 0
	s_barrier
	s_add_i32 s79, s67, s58
	v_lshl_add_u64 v[214:215], s[52:53], 0, v[130:131]
	s_mov_b32 m0, s79
	ds_read_b128 v[182:185], v146 offset:16384
	ds_read_b128 v[186:189], v146 offset:17408
	ds_read_b128 v[190:193], v146 offset:18432
	ds_read_b128 v[194:197], v146 offset:19456
	ds_read_b128 v[198:201], v146 offset:20480
	ds_read_b128 v[202:205], v146 offset:21504
	global_load_lds_dwordx4 v[214:215], off
	s_add_i32 m0, s79, 0x2000
	s_add_u32 s80, s52, 0x40000
	v_lshl_add_u64 v[216:217], s[52:53], 0, v[132:133]
	s_addc_u32 s81, s53, 0
	s_add_i32 s79, s68, s58
	global_load_lds_dwordx4 v[216:217], off
	v_lshl_add_u64 v[218:219], s[80:81], 0, v[130:131]
	s_mov_b32 m0, s79
	v_lshl_add_u64 v[220:221], s[54:55], 0, v[132:133]
	global_load_lds_dwordx4 v[218:219], off
	v_lshl_add_u64 v[218:219], s[80:81], 0, v[132:133]
	s_add_i32 m0, s79, 0x2000
	s_nop 0
	global_load_lds_dwordx4 v[218:219], off
	v_lshl_add_u64 v[218:219], s[54:55], 0, v[130:131]
	s_mov_b32 m0, s25
	s_nop 0
	global_load_lds_dwordx4 v[218:219], off
	s_mov_b32 m0, s60
	s_nop 0
	global_load_lds_dwordx4 v[220:221], off
	s_waitcnt vmcnt(8)
	s_waitcnt lgkmcnt(0)
	s_barrier
	s_setprio 1
	s_waitcnt lgkmcnt(0)
	v_mfma_f32_16x16x32_bf16 v[62:65], v[148:151], v[182:185], v[62:65]
	v_mfma_f32_16x16x32_bf16 v[58:61], v[156:159], v[182:185], v[58:61]
	v_mfma_f32_16x16x32_bf16 v[62:65], v[152:155], v[186:189], v[62:65]
	v_mfma_f32_16x16x32_bf16 v[58:61], v[160:163], v[186:189], v[58:61]
	v_mfma_f32_16x16x32_bf16 v[46:49], v[166:169], v[182:185], v[46:49]
	v_mfma_f32_16x16x32_bf16 v[42:45], v[174:177], v[182:185], v[42:45]
	v_mfma_f32_16x16x32_bf16 v[46:49], v[170:173], v[186:189], v[46:49]
	v_mfma_f32_16x16x32_bf16 v[42:45], v[178:181], v[186:189], v[42:45]
	v_mfma_f32_16x16x32_bf16 v[54:57], v[148:151], v[190:193], v[54:57]
	v_mfma_f32_16x16x32_bf16 v[50:53], v[156:159], v[190:193], v[50:53]
	v_mfma_f32_16x16x32_bf16 v[54:57], v[152:155], v[194:197], v[54:57]
	v_mfma_f32_16x16x32_bf16 v[50:53], v[160:163], v[194:197], v[50:53]
	v_mfma_f32_16x16x32_bf16 v[30:33], v[166:169], v[190:193], v[30:33]
	v_mfma_f32_16x16x32_bf16 v[26:29], v[174:177], v[190:193], v[26:29]
	v_mfma_f32_16x16x32_bf16 v[30:33], v[170:173], v[194:197], v[30:33]
	v_mfma_f32_16x16x32_bf16 v[26:29], v[178:181], v[194:197], v[26:29]
	s_cmp_eq_u32 s12, 0
	s_cbranch_scc1 .Lp7_sk1
	v_mfma_f32_16x16x32_bf16 v[38:41], v[148:151], v[198:201], v[38:41]
	v_mfma_f32_16x16x32_bf16 v[34:37], v[156:159], v[198:201], v[34:37]
	v_mfma_f32_16x16x32_bf16 v[38:41], v[152:155], v[202:205], v[38:41]
	v_mfma_f32_16x16x32_bf16 v[34:37], v[160:163], v[202:205], v[34:37]
	v_mfma_f32_16x16x32_bf16 v[14:17], v[166:169], v[198:201], v[14:17]
	v_mfma_f32_16x16x32_bf16 v[10:13], v[174:177], v[198:201], v[10:13]
	v_mfma_f32_16x16x32_bf16 v[14:17], v[170:173], v[202:205], v[14:17]
	v_mfma_f32_16x16x32_bf16 v[10:13], v[178:181], v[202:205], v[10:13]
.Lp7_sk1:
	s_setprio 0
	s_barrier
	s_add_i32 s79, 0, 0x18000
	v_add_u32_e32 v147, s79, v142
	s_add_i32 s80, 0, 0x1c000
	ds_read_b128 v[148:151], v147
	ds_read_b128 v[152:155], v147 offset:1024
	ds_read_b128 v[156:159], v147 offset:2048
	ds_read_b128 v[160:163], v147 offset:3072
	v_add_u32_e32 v147, s80, v142
	ds_read_b128 v[166:169], v147
	ds_read_b128 v[170:173], v147 offset:1024
	ds_read_b128 v[174:177], v147 offset:2048
	ds_read_b128 v[178:181], v147 offset:3072
	s_add_u32 s54, s54, 0x28000
	s_addc_u32 s55, s55, 0
	s_mov_b32 m0, s61
	v_lshl_add_u64 v[222:223], s[54:55], 0, v[130:131]
	ds_read_b128 v[182:185], v146 offset:32768
	ds_read_b128 v[186:189], v146 offset:33792
	ds_read_b128 v[190:193], v146 offset:34816
	ds_read_b128 v[194:197], v146 offset:35840
	ds_read_b128 v[198:201], v146 offset:36864
	ds_read_b128 v[202:205], v146 offset:37888
	global_load_lds_dwordx4 v[222:223], off
	v_lshl_add_u64 v[222:223], s[54:55], 0, v[132:133]
	s_mov_b32 m0, s62
	s_nop 0
	global_load_lds_dwordx4 v[222:223], off
	s_waitcnt vmcnt(8)
	s_waitcnt lgkmcnt(0)
	s_barrier
	s_setprio 1
	s_waitcnt lgkmcnt(0)
	v_mfma_f32_16x16x32_bf16 v[126:129], v[148:151], v[182:185], v[126:129]
	v_mfma_f32_16x16x32_bf16 v[122:125], v[156:159], v[182:185], v[122:125]
	v_mfma_f32_16x16x32_bf16 v[126:129], v[152:155], v[186:189], v[126:129]
	v_mfma_f32_16x16x32_bf16 v[122:125], v[160:163], v[186:189], v[122:125]
	v_mfma_f32_16x16x32_bf16 v[110:113], v[166:169], v[182:185], v[110:113]
	v_mfma_f32_16x16x32_bf16 v[106:109], v[174:177], v[182:185], v[106:109]
	v_mfma_f32_16x16x32_bf16 v[110:113], v[170:173], v[186:189], v[110:113]
	v_mfma_f32_16x16x32_bf16 v[106:109], v[178:181], v[186:189], v[106:109]
	v_mfma_f32_16x16x32_bf16 v[118:121], v[148:151], v[190:193], v[118:121]
	v_mfma_f32_16x16x32_bf16 v[114:117], v[156:159], v[190:193], v[114:117]
	v_mfma_f32_16x16x32_bf16 v[118:121], v[152:155], v[194:197], v[118:121]
	v_mfma_f32_16x16x32_bf16 v[114:117], v[160:163], v[194:197], v[114:117]
	v_mfma_f32_16x16x32_bf16 v[94:97], v[166:169], v[190:193], v[94:97]
	v_mfma_f32_16x16x32_bf16 v[90:93], v[174:177], v[190:193], v[90:93]
	v_mfma_f32_16x16x32_bf16 v[94:97], v[170:173], v[194:197], v[94:97]
	v_mfma_f32_16x16x32_bf16 v[90:93], v[178:181], v[194:197], v[90:93]
	s_cmp_eq_u32 s12, 0
	s_cbranch_scc1 .Lp7_sk2
	v_mfma_f32_16x16x32_bf16 v[102:105], v[148:151], v[198:201], v[102:105]
	v_mfma_f32_16x16x32_bf16 v[98:101], v[156:159], v[198:201], v[98:101]
	v_mfma_f32_16x16x32_bf16 v[102:105], v[152:155], v[202:205], v[102:105]
	v_mfma_f32_16x16x32_bf16 v[98:101], v[160:163], v[202:205], v[98:101]
	v_mfma_f32_16x16x32_bf16 v[78:81], v[166:169], v[198:201], v[78:81]
	v_mfma_f32_16x16x32_bf16 v[74:77], v[174:177], v[198:201], v[74:77]
	v_mfma_f32_16x16x32_bf16 v[78:81], v[170:173], v[202:205], v[78:81]
	v_mfma_f32_16x16x32_bf16 v[74:77], v[178:181], v[202:205], v[74:77]
.Lp7_sk2:
	s_setprio 0
	s_barrier
	s_add_i32 s54, s79, s58
	v_lshl_add_u64 v[214:215], v[214:215], 0, s[10:11]
	s_mov_b32 m0, s54
	ds_read_b128 v[182:185], v146 offset:49152
	ds_read_b128 v[186:189], v146 offset:50176
	ds_read_b128 v[190:193], v146 offset:51200
	ds_read_b128 v[194:197], v146 offset:52224
	ds_read_b128 v[198:201], v146 offset:53248
	ds_read_b128 v[202:205], v146 offset:54272
	global_load_lds_dwordx4 v[214:215], off
	s_add_i32 m0, s54, 0x2000
	s_add_u32 s52, s52, 0x40080
	v_lshl_add_u64 v[214:215], v[216:217], 0, s[10:11]
	s_addc_u32 s53, s53, 0
	s_add_i32 s54, s80, s58
	global_load_lds_dwordx4 v[214:215], off
	v_lshl_add_u64 v[214:215], s[52:53], 0, v[130:131]
	s_mov_b32 m0, s54
	s_nop 0
	global_load_lds_dwordx4 v[214:215], off
	v_lshl_add_u64 v[214:215], s[52:53], 0, v[132:133]
	s_add_i32 m0, s54, 0x2000
	s_nop 0
	global_load_lds_dwordx4 v[214:215], off
	v_lshl_add_u64 v[214:215], v[218:219], 0, s[10:11]
	s_mov_b32 m0, s65
	s_nop 0
	global_load_lds_dwordx4 v[214:215], off
	v_lshl_add_u64 v[214:215], v[220:221], 0, s[10:11]
	s_mov_b32 m0, s66
	s_nop 0
	global_load_lds_dwordx4 v[214:215], off
	s_waitcnt vmcnt(8)
	s_waitcnt lgkmcnt(0)
	s_barrier
	s_setprio 1
	s_waitcnt lgkmcnt(0)
	v_mfma_f32_16x16x32_bf16 v[62:65], v[148:151], v[182:185], v[62:65]
	v_mfma_f32_16x16x32_bf16 v[58:61], v[156:159], v[182:185], v[58:61]
	v_mfma_f32_16x16x32_bf16 v[62:65], v[152:155], v[186:189], v[62:65]
	v_mfma_f32_16x16x32_bf16 v[58:61], v[160:163], v[186:189], v[58:61]
	v_mfma_f32_16x16x32_bf16 v[46:49], v[166:169], v[182:185], v[46:49]
	v_mfma_f32_16x16x32_bf16 v[42:45], v[174:177], v[182:185], v[42:45]
	v_mfma_f32_16x16x32_bf16 v[46:49], v[170:173], v[186:189], v[46:49]
	v_mfma_f32_16x16x32_bf16 v[42:45], v[178:181], v[186:189], v[42:45]
	v_mfma_f32_16x16x32_bf16 v[54:57], v[148:151], v[190:193], v[54:57]
	v_mfma_f32_16x16x32_bf16 v[50:53], v[156:159], v[190:193], v[50:53]
	v_mfma_f32_16x16x32_bf16 v[54:57], v[152:155], v[194:197], v[54:57]
	v_mfma_f32_16x16x32_bf16 v[50:53], v[160:163], v[194:197], v[50:53]
	v_mfma_f32_16x16x32_bf16 v[30:33], v[166:169], v[190:193], v[30:33]
	v_mfma_f32_16x16x32_bf16 v[26:29], v[174:177], v[190:193], v[26:29]
	v_mfma_f32_16x16x32_bf16 v[30:33], v[170:173], v[194:197], v[30:33]
	v_mfma_f32_16x16x32_bf16 v[26:29], v[178:181], v[194:197], v[26:29]
	s_cmp_eq_u32 s12, 0
	s_cbranch_scc1 .Lp7_sk3
	v_mfma_f32_16x16x32_bf16 v[38:41], v[148:151], v[198:201], v[38:41]
	v_mfma_f32_16x16x32_bf16 v[34:37], v[156:159], v[198:201], v[34:37]
	v_mfma_f32_16x16x32_bf16 v[38:41], v[152:155], v[202:205], v[38:41]
	v_mfma_f32_16x16x32_bf16 v[34:37], v[160:163], v[202:205], v[34:37]
	v_mfma_f32_16x16x32_bf16 v[14:17], v[166:169], v[198:201], v[14:17]
	v_mfma_f32_16x16x32_bf16 v[10:13], v[174:177], v[198:201], v[10:13]
	v_mfma_f32_16x16x32_bf16 v[14:17], v[170:173], v[202:205], v[14:17]
	v_mfma_f32_16x16x32_bf16 v[10:13], v[178:181], v[202:205], v[10:13]
.Lp7_sk3:
	s_setprio 0
	s_barrier
	s_add_i32 s78, s78, 2
	s_add_u32 s50, s50, 0x100
	s_addc_u32 s51, s51, 0
	s_add_u32 s76, s76, 0x100
	s_addc_u32 s77, s77, 0
	s_cmp_gt_u32 s78, 13
	s_cbranch_scc0 .Lp7_loopB
	s_branch .Lp7_loopX
.Lp7_loopA:
	ds_read_b128 v[148:151], v144
	ds_read_b128 v[152:155], v144 offset:1024
	ds_read_b128 v[156:159], v144 offset:2048
	ds_read_b128 v[160:163], v144 offset:3072
	ds_read_b128 v[166:169], v145
	ds_read_b128 v[170:173], v145 offset:1024
	ds_read_b128 v[174:177], v145 offset:2048
	ds_read_b128 v[178:181], v145 offset:3072
	s_add_u32 s52, s50, 0xfffd8080
	s_addc_u32 s53, s51, -1
	s_cmp_eq_u32 s78, 12
	s_cselect_b32 s55, s45, s53
	s_cselect_b32 s54, s74, s52
	s_cselect_b32 s53, s23, s77
	s_cselect_b32 s52, s75, s76
	v_lshl_add_u64 v[214:215], s[50:51], 0, v[134:135]
	ds_read_b128 v[182:185], v146
	ds_read_b128 v[186:189], v146 offset:1024
	ds_read_b128 v[190:193], v146 offset:2048
	ds_read_b128 v[194:197], v146 offset:3072
	ds_read_b128 v[198:201], v146 offset:4096
	ds_read_b128 v[202:205], v146 offset:5120
	v_lshl_add_u64 v[214:215], s[50:51], 0, v[136:137]
	s_add_i32 m0, s25, 0xe000
	s_nop 0
	global_load_lds_dwordx4 v[214:215], off
	s_waitcnt vmcnt(6)
	s_waitcnt lgkmcnt(0)
	s_barrier
	s_setprio 1
	s_waitcnt lgkmcnt(0)
	v_mfma_f32_16x16x32_bf16 v[126:129], v[148:151], v[182:185], v[126:129]
	v_mfma_f32_16x16x32_bf16 v[122:125], v[156:159], v[182:185], v[122:125]
	v_mfma_f32_16x16x32_bf16 v[126:129], v[152:155], v[186:189], v[126:129]
	v_mfma_f32_16x16x32_bf16 v[122:125], v[160:163], v[186:189], v[122:125]
	v_mfma_f32_16x16x32_bf16 v[110:113], v[166:169], v[182:185], v[110:113]
	v_mfma_f32_16x16x32_bf16 v[106:109], v[174:177], v[182:185], v[106:109]
	v_mfma_f32_16x16x32_bf16 v[110:113], v[170:173], v[186:189], v[110:113]
	v_mfma_f32_16x16x32_bf16 v[106:109], v[178:181], v[186:189], v[106:109]
	v_mfma_f32_16x16x32_bf16 v[118:121], v[148:151], v[190:193], v[118:121]
	v_mfma_f32_16x16x32_bf16 v[114:117], v[156:159], v[190:193], v[114:117]
	v_mfma_f32_16x16x32_bf16 v[118:121], v[152:155], v[194:197], v[118:121]
	v_mfma_f32_16x16x32_bf16 v[114:117], v[160:163], v[194:197], v[114:117]
	v_mfma_f32_16x16x32_bf16 v[94:97], v[166:169], v[190:193], v[94:97]
	v_mfma_f32_16x16x32_bf16 v[90:93], v[174:177], v[190:193], v[90:93]
	v_mfma_f32_16x16x32_bf16 v[94:97], v[170:173], v[194:197], v[94:97]
	v_mfma_f32_16x16x32_bf16 v[90:93], v[178:181], v[194:197], v[90:93]
	s_cmp_eq_u32 s12, 0
	s_cbranch_scc1 .Lp7_skA0
	v_mfma_f32_16x16x32_bf16 v[102:105], v[148:151], v[198:201], v[102:105]
	v_mfma_f32_16x16x32_bf16 v[98:101], v[156:159], v[198:201], v[98:101]
	v_mfma_f32_16x16x32_bf16 v[102:105], v[152:155], v[202:205], v[102:105]
	v_mfma_f32_16x16x32_bf16 v[98:101], v[160:163], v[202:205], v[98:101]
	v_mfma_f32_16x16x32_bf16 v[78:81], v[166:169], v[198:201], v[78:81]
	v_mfma_f32_16x16x32_bf16 v[74:77], v[174:177], v[198:201], v[74:77]
	v_mfma_f32_16x16x32_bf16 v[78:81], v[170:173], v[202:205], v[78:81]
	v_mfma_f32_16x16x32_bf16 v[74:77], v[178:181], v[202:205], v[74:77]
.Lp7_skA0:
	s_setprio 0
	s_barrier
	s_add_i32 s79, s67, s58
	v_lshl_add_u64 v[214:215], s[52:53], 0, v[130:131]
	s_mov_b32 m0, s79
	ds_read_b128 v[182:185], v146 offset:16384
	ds_read_b128 v[186:189], v146 offset:17408
	ds_read_b128 v[190:193], v146 offset:18432
	ds_read_b128 v[194:197], v146 offset:19456
	ds_read_b128 v[198:201], v146 offset:20480
	ds_read_b128 v[202:205], v146 offset:21504
	global_load_lds_dwordx4 v[214:215], off
	s_add_i32 m0, s79, 0x2000
	s_add_u32 s80, s52, 0x40000
	v_lshl_add_u64 v[216:217], s[52:53], 0, v[132:133]
	s_addc_u32 s81, s53, 0
	s_add_i32 s79, s68, s58
	global_load_lds_dwordx4 v[216:217], off
	v_lshl_add_u64 v[218:219], s[80:81], 0, v[130:131]
	s_mov_b32 m0, s79
	v_lshl_add_u64 v[220:221], s[54:55], 0, v[132:133]
	global_load_lds_dwordx4 v[218:219], off
	v_lshl_add_u64 v[218:219], s[80:81], 0, v[132:133]
	s_add_i32 m0, s79, 0x2000
	s_nop 0
	global_load_lds_dwordx4 v[218:219], off
	v_lshl_add_u64 v[218:219], s[54:55], 0, v[130:131]
	s_nop 0
	s_mov_b32 m0, s60
	s_nop 0
	global_load_lds_dwordx4 v[220:221], off
	s_waitcnt vmcnt(6)
	s_waitcnt lgkmcnt(0)
	s_barrier
	s_setprio 1
	s_waitcnt lgkmcnt(0)
	v_mfma_f32_16x16x32_bf16 v[62:65], v[148:151], v[182:185], v[62:65]
	v_mfma_f32_16x16x32_bf16 v[58:61], v[156:159], v[182:185], v[58:61]
	v_mfma_f32_16x16x32_bf16 v[62:65], v[152:155], v[186:189], v[62:65]
	v_mfma_f32_16x16x32_bf16 v[58:61], v[160:163], v[186:189], v[58:61]
	v_mfma_f32_16x16x32_bf16 v[46:49], v[166:169], v[182:185], v[46:49]
	v_mfma_f32_16x16x32_bf16 v[42:45], v[174:177], v[182:185], v[42:45]
	v_mfma_f32_16x16x32_bf16 v[46:49], v[170:173], v[186:189], v[46:49]
	v_mfma_f32_16x16x32_bf16 v[42:45], v[178:181], v[186:189], v[42:45]
	v_mfma_f32_16x16x32_bf16 v[54:57], v[148:151], v[190:193], v[54:57]
	v_mfma_f32_16x16x32_bf16 v[50:53], v[156:159], v[190:193], v[50:53]
	v_mfma_f32_16x16x32_bf16 v[54:57], v[152:155], v[194:197], v[54:57]
	v_mfma_f32_16x16x32_bf16 v[50:53], v[160:163], v[194:197], v[50:53]
	v_mfma_f32_16x16x32_bf16 v[30:33], v[166:169], v[190:193], v[30:33]
	v_mfma_f32_16x16x32_bf16 v[26:29], v[174:177], v[190:193], v[26:29]
	v_mfma_f32_16x16x32_bf16 v[30:33], v[170:173], v[194:197], v[30:33]
	v_mfma_f32_16x16x32_bf16 v[26:29], v[178:181], v[194:197], v[26:29]
	s_cmp_eq_u32 s12, 0
	s_cbranch_scc1 .Lp7_skA1
	v_mfma_f32_16x16x32_bf16 v[38:41], v[148:151], v[198:201], v[38:41]
	v_mfma_f32_16x16x32_bf16 v[34:37], v[156:159], v[198:201], v[34:37]
	v_mfma_f32_16x16x32_bf16 v[38:41], v[152:155], v[202:205], v[38:41]
	v_mfma_f32_16x16x32_bf16 v[34:37], v[160:163], v[202:205], v[34:37]
	v_mfma_f32_16x16x32_bf16 v[14:17], v[166:169], v[198:201], v[14:17]
	v_mfma_f32_16x16x32_bf16 v[10:13], v[174:177], v[198:201], v[10:13]
	v_mfma_f32_16x16x32_bf16 v[14:17], v[170:173], v[202:205], v[14:17]
	v_mfma_f32_16x16x32_bf16 v[10:13], v[178:181], v[202:205], v[10:13]
.Lp7_skA1:
	s_setprio 0
	s_barrier
	s_add_i32 s79, 0, 0x18000
	v_add_u32_e32 v147, s79, v142
	s_add_i32 s80, 0, 0x1c000
	ds_read_b128 v[148:151], v147
	ds_read_b128 v[152:155], v147 offset:1024
	ds_read_b128 v[156:159], v147 offset:2048
	ds_read_b128 v[160:163], v147 offset:3072
	v_add_u32_e32 v147, s80, v142
	ds_read_b128 v[166:169], v147
	ds_read_b128 v[170:173], v147 offset:1024
	ds_read_b128 v[174:177], v147 offset:2048
	ds_read_b128 v[178:181], v147 offset:3072
	s_add_u32 s54, s54, 0x28000
	s_addc_u32 s55, s55, 0
	v_lshl_add_u64 v[222:223], s[54:55], 0, v[130:131]
	ds_read_b128 v[182:185], v146 offset:32768
	ds_read_b128 v[186:189], v146 offset:33792
	ds_read_b128 v[190:193], v146 offset:34816
	ds_read_b128 v[194:197], v146 offset:35840
	ds_read_b128 v[198:201], v146 offset:36864
	ds_read_b128 v[202:205], v146 offset:37888
	v_lshl_add_u64 v[222:223], s[54:55], 0, v[132:133]
	s_mov_b32 m0, s62
	s_nop 0
	global_load_lds_dwordx4 v[222:223], off
	s_waitcnt vmcnt(6)
	s_waitcnt lgkmcnt(0)
	s_barrier
	s_setprio 1
	s_waitcnt lgkmcnt(0)
	v_mfma_f32_16x16x32_bf16 v[126:129], v[148:151], v[182:185], v[126:129]
	v_mfma_f32_16x16x32_bf16 v[122:125], v[156:159], v[182:185], v[122:125]
	v_mfma_f32_16x16x32_bf16 v[126:129], v[152:155], v[186:189], v[126:129]
	v_mfma_f32_16x16x32_bf16 v[122:125], v[160:163], v[186:189], v[122:125]
	v_mfma_f32_16x16x32_bf16 v[110:113], v[166:169], v[182:185], v[110:113]
	v_mfma_f32_16x16x32_bf16 v[106:109], v[174:177], v[182:185], v[106:109]
	v_mfma_f32_16x16x32_bf16 v[110:113], v[170:173], v[186:189], v[110:113]
	v_mfma_f32_16x16x32_bf16 v[106:109], v[178:181], v[186:189], v[106:109]
	v_mfma_f32_16x16x32_bf16 v[118:121], v[148:151], v[190:193], v[118:121]
	v_mfma_f32_16x16x32_bf16 v[114:117], v[156:159], v[190:193], v[114:117]
	v_mfma_f32_16x16x32_bf16 v[118:121], v[152:155], v[194:197], v[118:121]
	v_mfma_f32_16x16x32_bf16 v[114:117], v[160:163], v[194:197], v[114:117]
	v_mfma_f32_16x16x32_bf16 v[94:97], v[166:169], v[190:193], v[94:97]
	v_mfma_f32_16x16x32_bf16 v[90:93], v[174:177], v[190:193], v[90:93]
	v_mfma_f32_16x16x32_bf16 v[94:97], v[170:173], v[194:197], v[94:97]
	v_mfma_f32_16x16x32_bf16 v[90:93], v[178:181], v[194:197], v[90:93]
	s_cmp_eq_u32 s12, 0
	s_cbranch_scc1 .Lp7_skA2
	v_mfma_f32_16x16x32_bf16 v[102:105], v[148:151], v[198:201], v[102:105]
	v_mfma_f32_16x16x32_bf16 v[98:101], v[156:159], v[198:201], v[98:101]
	v_mfma_f32_16x16x32_bf16 v[102:105], v[152:155], v[202:205], v[102:105]
	v_mfma_f32_16x16x32_bf16 v[98:101], v[160:163], v[202:205], v[98:101]
	v_mfma_f32_16x16x32_bf16 v[78:81], v[166:169], v[198:201], v[78:81]
	v_mfma_f32_16x16x32_bf16 v[74:77], v[174:177], v[198:201], v[74:77]
	v_mfma_f32_16x16x32_bf16 v[78:81], v[170:173], v[202:205], v[78:81]
	v_mfma_f32_16x16x32_bf16 v[74:77], v[178:181], v[202:205], v[74:77]
.Lp7_skA2:
	s_setprio 0
	s_barrier
	s_add_i32 s54, s79, s58
	v_lshl_add_u64 v[214:215], v[214:215], 0, s[10:11]
	s_mov_b32 m0, s54
	ds_read_b128 v[182:185], v146 offset:49152
	ds_read_b128 v[186:189], v146 offset:50176
	ds_read_b128 v[190:193], v146 offset:51200
	ds_read_b128 v[194:197], v146 offset:52224
	ds_read_b128 v[198:201], v146 offset:53248
	ds_read_b128 v[202:205], v146 offset:54272
	global_load_lds_dwordx4 v[214:215], off
	s_add_i32 m0, s54, 0x2000
	s_add_u32 s52, s52, 0x40080
	v_lshl_add_u64 v[214:215], v[216:217], 0, s[10:11]
	s_addc_u32 s53, s53, 0
	s_add_i32 s54, s80, s58
	global_load_lds_dwordx4 v[214:215], off
	v_lshl_add_u64 v[214:215], s[52:53], 0, v[130:131]
	s_mov_b32 m0, s54
	s_nop 0
	global_load_lds_dwordx4 v[214:215], off
	v_lshl_add_u64 v[214:215], s[52:53], 0, v[132:133]
	s_add_i32 m0, s54, 0x2000
	s_nop 0
	global_load_lds_dwordx4 v[214:215], off
	v_lshl_add_u64 v[214:215], v[218:219], 0, s[10:11]
	s_nop 0
	v_lshl_add_u64 v[214:215], v[220:221], 0, s[10:11]
	s_mov_b32 m0, s66
	s_nop 0
	global_load_lds_dwordx4 v[214:215], off
	s_waitcnt vmcnt(6)
	s_waitcnt lgkmcnt(0)
	s_barrier
	s_setprio 1
	s_waitcnt lgkmcnt(0)
	v_mfma_f32_16x16x32_bf16 v[62:65], v[148:151], v[182:185], v[62:65]
	v_mfma_f32_16x16x32_bf16 v[58:61], v[156:159], v[182:185], v[58:61]
	v_mfma_f32_16x16x32_bf16 v[62:65], v[152:155], v[186:189], v[62:65]
	v_mfma_f32_16x16x32_bf16 v[58:61], v[160:163], v[186:189], v[58:61]
	v_mfma_f32_16x16x32_bf16 v[46:49], v[166:169], v[182:185], v[46:49]
	v_mfma_f32_16x16x32_bf16 v[42:45], v[174:177], v[182:185], v[42:45]
	v_mfma_f32_16x16x32_bf16 v[46:49], v[170:173], v[186:189], v[46:49]
	v_mfma_f32_16x16x32_bf16 v[42:45], v[178:181], v[186:189], v[42:45]
	v_mfma_f32_16x16x32_bf16 v[54:57], v[148:151], v[190:193], v[54:57]
	v_mfma_f32_16x16x32_bf16 v[50:53], v[156:159], v[190:193], v[50:53]
	v_mfma_f32_16x16x32_bf16 v[54:57], v[152:155], v[194:197], v[54:57]
	v_mfma_f32_16x16x32_bf16 v[50:53], v[160:163], v[194:197], v[50:53]
	v_mfma_f32_16x16x32_bf16 v[30:33], v[166:169], v[190:193], v[30:33]
	v_mfma_f32_16x16x32_bf16 v[26:29], v[174:177], v[190:193], v[26:29]
	v_mfma_f32_16x16x32_bf16 v[30:33], v[170:173], v[194:197], v[30:33]
	v_mfma_f32_16x16x32_bf16 v[26:29], v[178:181], v[194:197], v[26:29]
	s_cmp_eq_u32 s12, 0
	s_cbranch_scc1 .Lp7_skA3
	v_mfma_f32_16x16x32_bf16 v[38:41], v[148:151], v[198:201], v[38:41]
	v_mfma_f32_16x16x32_bf16 v[34:37], v[156:159], v[198:201], v[34:37]
	v_mfma_f32_16x16x32_bf16 v[38:41], v[152:155], v[202:205], v[38:41]
	v_mfma_f32_16x16x32_bf16 v[34:37], v[160:163], v[202:205], v[34:37]
	v_mfma_f32_16x16x32_bf16 v[14:17], v[166:169], v[198:201], v[14:17]
	v_mfma_f32_16x16x32_bf16 v[10:13], v[174:177], v[198:201], v[10:13]
	v_mfma_f32_16x16x32_bf16 v[14:17], v[170:173], v[202:205], v[14:17]
	v_mfma_f32_16x16x32_bf16 v[10:13], v[178:181], v[202:205], v[10:13]
.Lp7_skA3:
	s_setprio 0
	s_barrier
	s_add_i32 s78, s78, 2
	s_add_u32 s50, s50, 0x100
	s_addc_u32 s51, s51, 0
	s_add_u32 s76, s76, 0x100
	s_addc_u32 s77, s77, 0
	s_cmp_gt_u32 s78, 13
	s_cbranch_scc0 .Lp7_loopA
.Lp7_loopX:
	s_and_b64 vcc, exec, s[12:13]
	s_cbranch_vccz .LBB0_837
	s_barrier
.LBB0_837:
	s_mul_i32 s98, s24, 0xa0
	v_lshl_or_b32 v216, s73, 8, v143
	v_add_u32_e32 v214, s98, v1
	v_ashrrev_i32_e32 v217, 31, v216
	v_ashrrev_i32_e32 v215, 31, v214
	v_lshlrev_b64 v[216:217], 1, v[216:217]
	v_lshlrev_b64 v[218:219], 11, v[214:215]
	v_lshl_add_u64 v[218:219], s[42:43], 0, v[218:219]
	v_lshl_add_u64 v[218:219], v[218:219], 0, v[216:217]
	v_cvt_pk_bf16_f32 v166, v126, v127
	v_cvt_pk_bf16_f32 v167, v128, v129
	v_cvt_pk_bf16_f32 v168, v122, v123
	v_cvt_pk_bf16_f32 v169, v124, v125
	global_store_dwordx4 v[218:219], v[166:169], off
	v_cvt_pk_bf16_f32 v170, v110, v111
	v_cvt_pk_bf16_f32 v171, v112, v113
	v_cvt_pk_bf16_f32 v172, v106, v107
	v_cvt_pk_bf16_f32 v173, v108, v109
	global_store_dwordx4 v[218:219], v[170:173], off offset:256
	v_mov_b32_e32 v148, 0x8000
	v_mov_b32_e32 v149, 0
	v_lshl_add_u64 v[148:149], v[218:219], 0, v[148:149]
	v_cvt_pk_bf16_f32 v174, v118, v119
	v_cvt_pk_bf16_f32 v175, v120, v121
	v_cvt_pk_bf16_f32 v176, v114, v115
	v_cvt_pk_bf16_f32 v177, v116, v117
	global_store_dwordx4 v[148:149], v[174:177], off
	v_cvt_pk_bf16_f32 v178, v94, v95
	v_cvt_pk_bf16_f32 v179, v96, v97
	v_cvt_pk_bf16_f32 v180, v90, v91
	v_cvt_pk_bf16_f32 v181, v92, v93
	global_store_dwordx4 v[148:149], v[178:181], off offset:256
	v_mov_b32_e32 v150, 0x28000
	v_mov_b32_e32 v151, 0
	v_lshl_add_u64 v[150:151], v[218:219], 0, v[150:151]
	v_cvt_pk_bf16_f32 v182, v62, v63
	v_cvt_pk_bf16_f32 v183, v64, v65
	v_cvt_pk_bf16_f32 v184, v58, v59
	v_cvt_pk_bf16_f32 v185, v60, v61
	global_store_dwordx4 v[150:151], v[182:185], off
	v_cvt_pk_bf16_f32 v186, v46, v47
	v_cvt_pk_bf16_f32 v187, v48, v49
	v_cvt_pk_bf16_f32 v188, v42, v43
	v_cvt_pk_bf16_f32 v189, v44, v45
	global_store_dwordx4 v[150:151], v[186:189], off offset:256
	v_mov_b32_e32 v152, 0x30000
	v_mov_b32_e32 v153, 0
	v_lshl_add_u64 v[152:153], v[218:219], 0, v[152:153]
	v_cvt_pk_bf16_f32 v190, v54, v55
	v_cvt_pk_bf16_f32 v191, v56, v57
	v_cvt_pk_bf16_f32 v192, v50, v51
	v_cvt_pk_bf16_f32 v193, v52, v53
	global_store_dwordx4 v[152:153], v[190:193], off
	v_cvt_pk_bf16_f32 v194, v30, v31
	v_cvt_pk_bf16_f32 v195, v32, v33
	v_cvt_pk_bf16_f32 v196, v26, v27
	v_cvt_pk_bf16_f32 v197, v28, v29
	global_store_dwordx4 v[152:153], v[194:197], off offset:256
	s_cmp_eq_u32 s12, 0
	s_cbranch_scc1 .Lp7_epi_done
	v_mov_b32_e32 v154, 0x10000
	v_mov_b32_e32 v155, 0
	v_lshl_add_u64 v[154:155], v[218:219], 0, v[154:155]
	v_cvt_pk_bf16_f32 v198, v102, v103
	v_cvt_pk_bf16_f32 v199, v104, v105
	v_cvt_pk_bf16_f32 v200, v98, v99
	v_cvt_pk_bf16_f32 v201, v100, v101
	global_store_dwordx4 v[154:155], v[198:201], off
	v_cvt_pk_bf16_f32 v202, v78, v79
	v_cvt_pk_bf16_f32 v203, v80, v81
	v_cvt_pk_bf16_f32 v204, v74, v75
	v_cvt_pk_bf16_f32 v205, v76, v77
	global_store_dwordx4 v[154:155], v[202:205], off offset:256
	v_mov_b32_e32 v156, 0x38000
	v_mov_b32_e32 v157, 0
	v_lshl_add_u64 v[156:157], v[218:219], 0, v[156:157]
	v_cvt_pk_bf16_f32 v206, v38, v39
	v_cvt_pk_bf16_f32 v207, v40, v41
	v_cvt_pk_bf16_f32 v208, v34, v35
	v_cvt_pk_bf16_f32 v209, v36, v37
	global_store_dwordx4 v[156:157], v[206:209], off
	v_cvt_pk_bf16_f32 v210, v14, v15
	v_cvt_pk_bf16_f32 v211, v16, v17
	v_cvt_pk_bf16_f32 v212, v10, v11
	v_cvt_pk_bf16_f32 v213, v12, v13
	global_store_dwordx4 v[156:157], v[210:213], off offset:256
.Lp7_epi_done:
	s_andn2_b64 vcc, exec, s[0:1]
	s_mov_b64 s[0:1], -1
	s_cbranch_vccnz .LBB0_830
	s_andn2_b64 vcc, exec, s[8:9]
	s_cbranch_vccnz .LBB0_829
	s_barrier
	s_branch .LBB0_829

.LBB0_1048:
	s_lshl_b32 s5, s5, 5
	s_mov_b64 s[10:11], 0x80
	s_and_b32 s5, s5, 0x60
	s_add_i32 m0, s50, 0x18000
	v_lshl_add_u64 v[8:9], v[8:9], 0, s[10:11]
	s_ashr_i32 s55, s3, 31
	s_lshl_b32 s14, s1, 13
	s_lshl_b32 s15, s5, 7
	s_waitcnt vmcnt(2)
	s_barrier
	global_load_lds_dwordx4 v[8:9], off
	v_lshl_add_u64 v[6:7], v[6:7], 0, s[10:11]
	s_add_i32 m0, s50, 0x1a000
	s_add_i32 s56, s50, 0x8000
	s_add_i32 s57, s50, 0xa000
	global_load_lds_dwordx4 v[6:7], off
	v_lshl_add_u64 v[2:3], v[2:3], 0, s[10:11]
	s_mov_b32 m0, s56
	s_add_u32 s12, s44, 0xb0080
	global_load_lds_dwordx4 v[2:3], off
	v_lshl_add_u64 v[2:3], v[4:5], 0, s[10:11]
	s_mov_b32 m0, s57
	s_addc_u32 s13, s45, 0
	global_load_lds_dwordx4 v[2:3], off
	s_add_i32 m0, s50, 0x1c000
	v_lshl_add_u64 v[2:3], s[12:13], 0, v[128:129]
	global_load_lds_dwordx4 v[2:3], off
	v_lshl_add_u64 v[2:3], s[12:13], 0, v[130:131]
	s_add_i32 m0, s50, 0x1e000
	s_sext_i32_i8 s67, s4
	global_load_lds_dwordx4 v[2:3], off
	v_lshrrev_b32_e32 v3, 1, v0
	v_and_b32_e32 v3, 24, v3
	v_and_b32_e32 v2, 15, v0
	v_lshlrev_b32_e32 v4, 1, v3
	v_lshlrev_b32_e32 v5, 6, v0
	s_movk_i32 s4, 0x3c0
	v_lshlrev_b32_e32 v0, 2, v0
	v_and_or_b32 v5, v5, s4, v4
	v_and_b32_e32 v0, 32, v0
	v_mad_u32_u24 v140, s1, 48, v2
	v_lshl_or_b32 v2, v2, 6, v4
	s_waitcnt vmcnt(6)
	s_cmpk_lt_u32 s0, 0x100
	v_bitop3_b32 v2, v2, s14, v0 bitop3:0xde
	v_bitop3_b32 v141, s15, v5, v0 bitop3:0xf6
	s_cselect_b64 s[12:13], -1, 0
	s_add_i32 s58, 0, 0x10000
	s_add_i32 s59, 0, 0x14000
	v_or_b32_e32 v142, s5, v3
	v_add3_u32 v132, v11, v1, v10
	v_mov_b32_e32 v133, v129
	v_add3_u32 v134, v12, v1, v10
	v_mov_b32_e32 v135, v129
	v_mov_b64_e32 v[136:137], 0x100
	v_mov_b64_e32 v[138:139], 0xff
	v_add_u32_e32 v143, s58, v141
	v_add_u32_e32 v144, s59, v141
	s_movk_i32 s98, 0x1800
	s_cmp_eq_u32 s1, 1
	s_cselect_b32 s98, 0x1000, s98
	v_add_u32_e32 v145, s98, v2
	s_mov_b64 s[14:15], 0x40000
	s_mov_b32 s60, 0x40000
	s_mov_b64 s[18:19], 0x48000
	s_mov_b32 s61, 0x48000
	s_mov_b64 s[20:21], 0x50000
	s_mov_b32 s62, 0x50000
	s_mov_b64 s[22:23], 0x58000
	s_mov_b32 s63, 0x58000
	s_barrier
	s_waitcnt vmcnt(0)
	s_branch .LBB0_1051

.LBB0_1058:
	s_cmp_lt_u32 s48, 0x1800
	s_cbranch_scc1 .Lp10_loopA
.Lp10_loopB:
	ds_read_b128 v[146:149], v143
	ds_read_b128 v[150:153], v143 offset:1024
	ds_read_b128 v[154:157], v143 offset:2048
	ds_read_b128 v[158:161], v143 offset:3072
	ds_read_b128 v[166:169], v144
	ds_read_b128 v[170:173], v144 offset:1024
	ds_read_b128 v[174:177], v144 offset:2048
	ds_read_b128 v[178:181], v144 offset:3072
	s_add_u32 s44, s36, 0xfff92080
	s_addc_u32 s45, s37, -1
	s_cmp_eq_u32 s70, 40
	s_cselect_b32 s47, s1, s45
	s_cselect_b32 s46, s0, s44
	s_cselect_b32 s45, s25, s69
	s_cselect_b32 s44, s24, s68
	v_lshl_add_u64 v[162:163], s[36:37], 0, v[132:133]
	s_add_i32 m0, s50, 0xc000
	ds_read_b128 v[182:185], v145
	ds_read_b128 v[186:189], v145 offset:1024
	ds_read_b128 v[190:193], v145 offset:2048
	ds_read_b128 v[194:197], v145 offset:3072
	ds_read_b128 v[198:201], v145 offset:4096
	ds_read_b128 v[202:205], v145 offset:5120
	global_load_lds_dwordx4 v[162:163], off
	v_lshl_add_u64 v[162:163], s[36:37], 0, v[134:135]
	s_add_i32 m0, s50, 0xe000
	s_nop 0
	global_load_lds_dwordx4 v[162:163], off
	s_waitcnt vmcnt(8)
	s_waitcnt lgkmcnt(0)
	s_barrier
	s_setprio 1
	s_waitcnt lgkmcnt(0)
	v_mfma_f32_16x16x32_bf16 v[124:127], v[146:149], v[182:185], v[124:127]
	v_mfma_f32_16x16x32_bf16 v[120:123], v[154:157], v[182:185], v[120:123]
	v_mfma_f32_16x16x32_bf16 v[124:127], v[150:153], v[186:189], v[124:127]
	v_mfma_f32_16x16x32_bf16 v[120:123], v[158:161], v[186:189], v[120:123]
	v_mfma_f32_16x16x32_bf16 v[108:111], v[166:169], v[182:185], v[108:111]
	v_mfma_f32_16x16x32_bf16 v[104:107], v[174:177], v[182:185], v[104:107]
	v_mfma_f32_16x16x32_bf16 v[108:111], v[170:173], v[186:189], v[108:111]
	v_mfma_f32_16x16x32_bf16 v[104:107], v[178:181], v[186:189], v[104:107]
	v_mfma_f32_16x16x32_bf16 v[116:119], v[146:149], v[190:193], v[116:119]
	v_mfma_f32_16x16x32_bf16 v[112:115], v[154:157], v[190:193], v[112:115]
	v_mfma_f32_16x16x32_bf16 v[116:119], v[150:153], v[194:197], v[116:119]
	v_mfma_f32_16x16x32_bf16 v[112:115], v[158:161], v[194:197], v[112:115]
	v_mfma_f32_16x16x32_bf16 v[92:95], v[166:169], v[190:193], v[92:95]
	v_mfma_f32_16x16x32_bf16 v[88:91], v[174:177], v[190:193], v[88:91]
	v_mfma_f32_16x16x32_bf16 v[92:95], v[170:173], v[194:197], v[92:95]
	v_mfma_f32_16x16x32_bf16 v[88:91], v[178:181], v[194:197], v[88:91]
	s_cmp_eq_u32 s12, 0
	s_cbranch_scc1 .Lp10_sk0
	v_mfma_f32_16x16x32_bf16 v[100:103], v[146:149], v[198:201], v[100:103]
	v_mfma_f32_16x16x32_bf16 v[96:99], v[154:157], v[198:201], v[96:99]
	v_mfma_f32_16x16x32_bf16 v[100:103], v[150:153], v[202:205], v[100:103]
	v_mfma_f32_16x16x32_bf16 v[96:99], v[158:161], v[202:205], v[96:99]
	v_mfma_f32_16x16x32_bf16 v[76:79], v[166:169], v[198:201], v[76:79]
	v_mfma_f32_16x16x32_bf16 v[72:75], v[174:177], v[198:201], v[72:75]
	v_mfma_f32_16x16x32_bf16 v[76:79], v[170:173], v[202:205], v[76:79]
	v_mfma_f32_16x16x32_bf16 v[72:75], v[178:181], v[202:205], v[72:75]
.Lp10_sk0:
	s_setprio 0
	s_barrier
	s_add_i32 s71, s58, s48
	v_lshl_add_u64 v[162:163], s[44:45], 0, v[128:129]
	s_mov_b32 m0, s71
	ds_read_b128 v[182:185], v145 offset:16384
	ds_read_b128 v[186:189], v145 offset:17408
	ds_read_b128 v[190:193], v145 offset:18432
	ds_read_b128 v[194:197], v145 offset:19456
	ds_read_b128 v[198:201], v145 offset:20480
	ds_read_b128 v[202:205], v145 offset:21504
	global_load_lds_dwordx4 v[162:163], off
	s_add_i32 m0, s71, 0x2000
	s_add_u32 s72, s44, 0xb0000
	v_lshl_add_u64 v[214:215], s[44:45], 0, v[130:131]
	s_addc_u32 s73, s45, 0
	s_add_i32 s71, s59, s48
	global_load_lds_dwordx4 v[214:215], off
	v_lshl_add_u64 v[216:217], s[72:73], 0, v[128:129]
	s_mov_b32 m0, s71
	v_lshl_add_u64 v[218:219], s[46:47], 0, v[130:131]
	global_load_lds_dwordx4 v[216:217], off
	v_lshl_add_u64 v[216:217], s[72:73], 0, v[130:131]
	s_add_i32 m0, s71, 0x2000
	s_nop 0
	global_load_lds_dwordx4 v[216:217], off
	v_lshl_add_u64 v[216:217], s[46:47], 0, v[128:129]
	s_mov_b32 m0, s50
	s_nop 0
	global_load_lds_dwordx4 v[216:217], off
	s_mov_b32 m0, s51
	s_nop 0
	global_load_lds_dwordx4 v[218:219], off
	s_waitcnt vmcnt(8)
	s_waitcnt lgkmcnt(0)
	s_barrier
	s_setprio 1
	s_waitcnt lgkmcnt(0)
	v_mfma_f32_16x16x32_bf16 v[60:63], v[146:149], v[182:185], v[60:63]
	v_mfma_f32_16x16x32_bf16 v[56:59], v[154:157], v[182:185], v[56:59]
	v_mfma_f32_16x16x32_bf16 v[60:63], v[150:153], v[186:189], v[60:63]
	v_mfma_f32_16x16x32_bf16 v[56:59], v[158:161], v[186:189], v[56:59]
	v_mfma_f32_16x16x32_bf16 v[44:47], v[166:169], v[182:185], v[44:47]
	v_mfma_f32_16x16x32_bf16 v[40:43], v[174:177], v[182:185], v[40:43]
	v_mfma_f32_16x16x32_bf16 v[44:47], v[170:173], v[186:189], v[44:47]
	v_mfma_f32_16x16x32_bf16 v[40:43], v[178:181], v[186:189], v[40:43]
	v_mfma_f32_16x16x32_bf16 v[52:55], v[146:149], v[190:193], v[52:55]
	v_mfma_f32_16x16x32_bf16 v[48:51], v[154:157], v[190:193], v[48:51]
	v_mfma_f32_16x16x32_bf16 v[52:55], v[150:153], v[194:197], v[52:55]
	v_mfma_f32_16x16x32_bf16 v[48:51], v[158:161], v[194:197], v[48:51]
	v_mfma_f32_16x16x32_bf16 v[28:31], v[166:169], v[190:193], v[28:31]
	v_mfma_f32_16x16x32_bf16 v[24:27], v[174:177], v[190:193], v[24:27]
	v_mfma_f32_16x16x32_bf16 v[28:31], v[170:173], v[194:197], v[28:31]
	v_mfma_f32_16x16x32_bf16 v[24:27], v[178:181], v[194:197], v[24:27]
	s_cmp_eq_u32 s12, 0
	s_cbranch_scc1 .Lp10_sk1
	v_mfma_f32_16x16x32_bf16 v[36:39], v[146:149], v[198:201], v[36:39]
	v_mfma_f32_16x16x32_bf16 v[32:35], v[154:157], v[198:201], v[32:35]
	v_mfma_f32_16x16x32_bf16 v[36:39], v[150:153], v[202:205], v[36:39]
	v_mfma_f32_16x16x32_bf16 v[32:35], v[158:161], v[202:205], v[32:35]
	v_mfma_f32_16x16x32_bf16 v[12:15], v[166:169], v[198:201], v[12:15]
	v_mfma_f32_16x16x32_bf16 v[8:11], v[174:177], v[198:201], v[8:11]
	v_mfma_f32_16x16x32_bf16 v[12:15], v[170:173], v[202:205], v[12:15]
	v_mfma_f32_16x16x32_bf16 v[8:11], v[178:181], v[202:205], v[8:11]
.Lp10_sk1:
	s_setprio 0
	s_barrier
	s_add_i32 s71, 0, 0x18000
	s_add_i32 s72, 0, 0x1c000
	v_add_u32_e32 v158, s71, v141
	v_add_u32_e32 v165, s72, v141
	ds_read_b128 v[146:149], v158
	ds_read_b128 v[150:153], v158 offset:1024
	ds_read_b128 v[154:157], v158 offset:2048
	ds_read_b128 v[158:161], v158 offset:3072
	ds_read_b128 v[166:169], v165
	ds_read_b128 v[170:173], v165 offset:1024
	ds_read_b128 v[174:177], v165 offset:2048
	ds_read_b128 v[178:181], v165 offset:3072
	s_add_u32 s46, s46, 0x6e000
	s_addc_u32 s47, s47, 0
	s_mov_b32 m0, s52
	v_lshl_add_u64 v[220:221], s[46:47], 0, v[128:129]
	ds_read_b128 v[182:185], v145 offset:32768
	ds_read_b128 v[186:189], v145 offset:33792
	ds_read_b128 v[190:193], v145 offset:34816
	ds_read_b128 v[194:197], v145 offset:35840
	ds_read_b128 v[198:201], v145 offset:36864
	ds_read_b128 v[202:205], v145 offset:37888
	global_load_lds_dwordx4 v[220:221], off
	v_lshl_add_u64 v[220:221], s[46:47], 0, v[130:131]
	s_mov_b32 m0, s53
	s_nop 0
	global_load_lds_dwordx4 v[220:221], off
	s_waitcnt vmcnt(8)
	s_waitcnt lgkmcnt(0)
	s_barrier
	s_setprio 1
	s_waitcnt lgkmcnt(0)
	v_mfma_f32_16x16x32_bf16 v[124:127], v[146:149], v[182:185], v[124:127]
	v_mfma_f32_16x16x32_bf16 v[120:123], v[154:157], v[182:185], v[120:123]
	v_mfma_f32_16x16x32_bf16 v[124:127], v[150:153], v[186:189], v[124:127]
	v_mfma_f32_16x16x32_bf16 v[120:123], v[158:161], v[186:189], v[120:123]
	v_mfma_f32_16x16x32_bf16 v[108:111], v[166:169], v[182:185], v[108:111]
	v_mfma_f32_16x16x32_bf16 v[104:107], v[174:177], v[182:185], v[104:107]
	v_mfma_f32_16x16x32_bf16 v[108:111], v[170:173], v[186:189], v[108:111]
	v_mfma_f32_16x16x32_bf16 v[104:107], v[178:181], v[186:189], v[104:107]
	v_mfma_f32_16x16x32_bf16 v[116:119], v[146:149], v[190:193], v[116:119]
	v_mfma_f32_16x16x32_bf16 v[112:115], v[154:157], v[190:193], v[112:115]
	v_mfma_f32_16x16x32_bf16 v[116:119], v[150:153], v[194:197], v[116:119]
	v_mfma_f32_16x16x32_bf16 v[112:115], v[158:161], v[194:197], v[112:115]
	v_mfma_f32_16x16x32_bf16 v[92:95], v[166:169], v[190:193], v[92:95]
	v_mfma_f32_16x16x32_bf16 v[88:91], v[174:177], v[190:193], v[88:91]
	v_mfma_f32_16x16x32_bf16 v[92:95], v[170:173], v[194:197], v[92:95]
	v_mfma_f32_16x16x32_bf16 v[88:91], v[178:181], v[194:197], v[88:91]
	s_cmp_eq_u32 s12, 0
	s_cbranch_scc1 .Lp10_sk2
	v_mfma_f32_16x16x32_bf16 v[100:103], v[146:149], v[198:201], v[100:103]
	v_mfma_f32_16x16x32_bf16 v[96:99], v[154:157], v[198:201], v[96:99]
	v_mfma_f32_16x16x32_bf16 v[100:103], v[150:153], v[202:205], v[100:103]
	v_mfma_f32_16x16x32_bf16 v[96:99], v[158:161], v[202:205], v[96:99]
	v_mfma_f32_16x16x32_bf16 v[76:79], v[166:169], v[198:201], v[76:79]
	v_mfma_f32_16x16x32_bf16 v[72:75], v[174:177], v[198:201], v[72:75]
	v_mfma_f32_16x16x32_bf16 v[76:79], v[170:173], v[202:205], v[76:79]
	v_mfma_f32_16x16x32_bf16 v[72:75], v[178:181], v[202:205], v[72:75]
.Lp10_sk2:
	s_setprio 0
	s_barrier
	s_add_i32 s46, s71, s48
	v_lshl_add_u64 v[162:163], v[162:163], 0, s[10:11]
	s_mov_b32 m0, s46
	ds_read_b128 v[182:185], v145 offset:49152
	ds_read_b128 v[186:189], v145 offset:50176
	ds_read_b128 v[190:193], v145 offset:51200
	ds_read_b128 v[194:197], v145 offset:52224
	ds_read_b128 v[198:201], v145 offset:53248
	ds_read_b128 v[202:205], v145 offset:54272
	global_load_lds_dwordx4 v[162:163], off
	s_add_i32 m0, s46, 0x2000
	s_add_u32 s44, s44, 0xb0080
	v_lshl_add_u64 v[162:163], v[214:215], 0, s[10:11]
	s_addc_u32 s45, s45, 0
	s_add_i32 s46, s72, s48
	global_load_lds_dwordx4 v[162:163], off
	v_lshl_add_u64 v[162:163], s[44:45], 0, v[128:129]
	s_mov_b32 m0, s46
	s_nop 0
	global_load_lds_dwordx4 v[162:163], off
	v_lshl_add_u64 v[162:163], s[44:45], 0, v[130:131]
	s_add_i32 m0, s46, 0x2000
	s_nop 0
	global_load_lds_dwordx4 v[162:163], off
	v_lshl_add_u64 v[162:163], v[216:217], 0, s[10:11]
	s_mov_b32 m0, s56
	s_nop 0
	global_load_lds_dwordx4 v[162:163], off
	v_lshl_add_u64 v[162:163], v[218:219], 0, s[10:11]
	s_mov_b32 m0, s57
	s_nop 0
	global_load_lds_dwordx4 v[162:163], off
	s_waitcnt vmcnt(8)
	s_waitcnt lgkmcnt(0)
	s_barrier
	s_setprio 1
	s_waitcnt lgkmcnt(0)
	v_mfma_f32_16x16x32_bf16 v[60:63], v[146:149], v[182:185], v[60:63]
	v_mfma_f32_16x16x32_bf16 v[56:59], v[154:157], v[182:185], v[56:59]
	v_mfma_f32_16x16x32_bf16 v[60:63], v[150:153], v[186:189], v[60:63]
	v_mfma_f32_16x16x32_bf16 v[56:59], v[158:161], v[186:189], v[56:59]
	v_mfma_f32_16x16x32_bf16 v[44:47], v[166:169], v[182:185], v[44:47]
	v_mfma_f32_16x16x32_bf16 v[40:43], v[174:177], v[182:185], v[40:43]
	v_mfma_f32_16x16x32_bf16 v[44:47], v[170:173], v[186:189], v[44:47]
	v_mfma_f32_16x16x32_bf16 v[40:43], v[178:181], v[186:189], v[40:43]
	v_mfma_f32_16x16x32_bf16 v[52:55], v[146:149], v[190:193], v[52:55]
	v_mfma_f32_16x16x32_bf16 v[48:51], v[154:157], v[190:193], v[48:51]
	v_mfma_f32_16x16x32_bf16 v[52:55], v[150:153], v[194:197], v[52:55]
	v_mfma_f32_16x16x32_bf16 v[48:51], v[158:161], v[194:197], v[48:51]
	v_mfma_f32_16x16x32_bf16 v[28:31], v[166:169], v[190:193], v[28:31]
	v_mfma_f32_16x16x32_bf16 v[24:27], v[174:177], v[190:193], v[24:27]
	v_mfma_f32_16x16x32_bf16 v[28:31], v[170:173], v[194:197], v[28:31]
	v_mfma_f32_16x16x32_bf16 v[24:27], v[178:181], v[194:197], v[24:27]
	s_cmp_eq_u32 s12, 0
	s_cbranch_scc1 .Lp10_sk3
	v_mfma_f32_16x16x32_bf16 v[36:39], v[146:149], v[198:201], v[36:39]
	v_mfma_f32_16x16x32_bf16 v[32:35], v[154:157], v[198:201], v[32:35]
	v_mfma_f32_16x16x32_bf16 v[36:39], v[150:153], v[202:205], v[36:39]
	v_mfma_f32_16x16x32_bf16 v[32:35], v[158:161], v[202:205], v[32:35]
	v_mfma_f32_16x16x32_bf16 v[12:15], v[166:169], v[198:201], v[12:15]
	v_mfma_f32_16x16x32_bf16 v[8:11], v[174:177], v[198:201], v[8:11]
	v_mfma_f32_16x16x32_bf16 v[12:15], v[170:173], v[202:205], v[12:15]
	v_mfma_f32_16x16x32_bf16 v[8:11], v[178:181], v[202:205], v[8:11]
.Lp10_sk3:
	s_setprio 0
	s_barrier
	s_add_i32 s70, s70, 2
	s_add_u32 s36, s36, 0x100
	s_addc_u32 s37, s37, 0
	s_add_u32 s68, s68, 0x100
	s_addc_u32 s69, s69, 0
	s_cmp_gt_u32 s70, 41
	s_cbranch_scc0 .Lp10_loopB
	s_branch .Lp10_loopX
.Lp10_loopA:
	ds_read_b128 v[146:149], v143
	ds_read_b128 v[150:153], v143 offset:1024
	ds_read_b128 v[154:157], v143 offset:2048
	ds_read_b128 v[158:161], v143 offset:3072
	ds_read_b128 v[166:169], v144
	ds_read_b128 v[170:173], v144 offset:1024
	ds_read_b128 v[174:177], v144 offset:2048
	ds_read_b128 v[178:181], v144 offset:3072
	s_add_u32 s44, s36, 0xfff92080
	s_addc_u32 s45, s37, -1
	s_cmp_eq_u32 s70, 40
	s_cselect_b32 s47, s1, s45
	s_cselect_b32 s46, s0, s44
	s_cselect_b32 s45, s25, s69
	s_cselect_b32 s44, s24, s68
	v_lshl_add_u64 v[162:163], s[36:37], 0, v[132:133]
	ds_read_b128 v[182:185], v145
	ds_read_b128 v[186:189], v145 offset:1024
	ds_read_b128 v[190:193], v145 offset:2048
	ds_read_b128 v[194:197], v145 offset:3072
	ds_read_b128 v[198:201], v145 offset:4096
	ds_read_b128 v[202:205], v145 offset:5120
	v_lshl_add_u64 v[162:163], s[36:37], 0, v[134:135]
	s_add_i32 m0, s50, 0xe000
	s_nop 0
	global_load_lds_dwordx4 v[162:163], off
	s_waitcnt vmcnt(6)
	s_waitcnt lgkmcnt(0)
	s_barrier
	s_setprio 1
	s_waitcnt lgkmcnt(0)
	v_mfma_f32_16x16x32_bf16 v[124:127], v[146:149], v[182:185], v[124:127]
	v_mfma_f32_16x16x32_bf16 v[120:123], v[154:157], v[182:185], v[120:123]
	v_mfma_f32_16x16x32_bf16 v[124:127], v[150:153], v[186:189], v[124:127]
	v_mfma_f32_16x16x32_bf16 v[120:123], v[158:161], v[186:189], v[120:123]
	v_mfma_f32_16x16x32_bf16 v[108:111], v[166:169], v[182:185], v[108:111]
	v_mfma_f32_16x16x32_bf16 v[104:107], v[174:177], v[182:185], v[104:107]
	v_mfma_f32_16x16x32_bf16 v[108:111], v[170:173], v[186:189], v[108:111]
	v_mfma_f32_16x16x32_bf16 v[104:107], v[178:181], v[186:189], v[104:107]
	v_mfma_f32_16x16x32_bf16 v[116:119], v[146:149], v[190:193], v[116:119]
	v_mfma_f32_16x16x32_bf16 v[112:115], v[154:157], v[190:193], v[112:115]
	v_mfma_f32_16x16x32_bf16 v[116:119], v[150:153], v[194:197], v[116:119]
	v_mfma_f32_16x16x32_bf16 v[112:115], v[158:161], v[194:197], v[112:115]
	v_mfma_f32_16x16x32_bf16 v[92:95], v[166:169], v[190:193], v[92:95]
	v_mfma_f32_16x16x32_bf16 v[88:91], v[174:177], v[190:193], v[88:91]
	v_mfma_f32_16x16x32_bf16 v[92:95], v[170:173], v[194:197], v[92:95]
	v_mfma_f32_16x16x32_bf16 v[88:91], v[178:181], v[194:197], v[88:91]
	s_cmp_eq_u32 s12, 0
	s_cbranch_scc1 .Lp10_skA0
	v_mfma_f32_16x16x32_bf16 v[100:103], v[146:149], v[198:201], v[100:103]
	v_mfma_f32_16x16x32_bf16 v[96:99], v[154:157], v[198:201], v[96:99]
	v_mfma_f32_16x16x32_bf16 v[100:103], v[150:153], v[202:205], v[100:103]
	v_mfma_f32_16x16x32_bf16 v[96:99], v[158:161], v[202:205], v[96:99]
	v_mfma_f32_16x16x32_bf16 v[76:79], v[166:169], v[198:201], v[76:79]
	v_mfma_f32_16x16x32_bf16 v[72:75], v[174:177], v[198:201], v[72:75]
	v_mfma_f32_16x16x32_bf16 v[76:79], v[170:173], v[202:205], v[76:79]
	v_mfma_f32_16x16x32_bf16 v[72:75], v[178:181], v[202:205], v[72:75]
.Lp10_skA0:
	s_setprio 0
	s_barrier
	s_add_i32 s71, s58, s48
	v_lshl_add_u64 v[162:163], s[44:45], 0, v[128:129]
	s_mov_b32 m0, s71
	ds_read_b128 v[182:185], v145 offset:16384
	ds_read_b128 v[186:189], v145 offset:17408
	ds_read_b128 v[190:193], v145 offset:18432
	ds_read_b128 v[194:197], v145 offset:19456
	ds_read_b128 v[198:201], v145 offset:20480
	ds_read_b128 v[202:205], v145 offset:21504
	global_load_lds_dwordx4 v[162:163], off
	s_add_i32 m0, s71, 0x2000
	s_add_u32 s72, s44, 0xb0000
	v_lshl_add_u64 v[214:215], s[44:45], 0, v[130:131]
	s_addc_u32 s73, s45, 0
	s_add_i32 s71, s59, s48
	global_load_lds_dwordx4 v[214:215], off
	v_lshl_add_u64 v[216:217], s[72:73], 0, v[128:129]
	s_mov_b32 m0, s71
	v_lshl_add_u64 v[218:219], s[46:47], 0, v[130:131]
	global_load_lds_dwordx4 v[216:217], off
	v_lshl_add_u64 v[216:217], s[72:73], 0, v[130:131]
	s_add_i32 m0, s71, 0x2000
	s_nop 0
	global_load_lds_dwordx4 v[216:217], off
	v_lshl_add_u64 v[216:217], s[46:47], 0, v[128:129]
	s_nop 0
	s_mov_b32 m0, s51
	s_nop 0
	global_load_lds_dwordx4 v[218:219], off
	s_waitcnt vmcnt(6)
	s_waitcnt lgkmcnt(0)
	s_barrier
	s_setprio 1
	s_waitcnt lgkmcnt(0)
	v_mfma_f32_16x16x32_bf16 v[60:63], v[146:149], v[182:185], v[60:63]
	v_mfma_f32_16x16x32_bf16 v[56:59], v[154:157], v[182:185], v[56:59]
	v_mfma_f32_16x16x32_bf16 v[60:63], v[150:153], v[186:189], v[60:63]
	v_mfma_f32_16x16x32_bf16 v[56:59], v[158:161], v[186:189], v[56:59]
	v_mfma_f32_16x16x32_bf16 v[44:47], v[166:169], v[182:185], v[44:47]
	v_mfma_f32_16x16x32_bf16 v[40:43], v[174:177], v[182:185], v[40:43]
	v_mfma_f32_16x16x32_bf16 v[44:47], v[170:173], v[186:189], v[44:47]
	v_mfma_f32_16x16x32_bf16 v[40:43], v[178:181], v[186:189], v[40:43]
	v_mfma_f32_16x16x32_bf16 v[52:55], v[146:149], v[190:193], v[52:55]
	v_mfma_f32_16x16x32_bf16 v[48:51], v[154:157], v[190:193], v[48:51]
	v_mfma_f32_16x16x32_bf16 v[52:55], v[150:153], v[194:197], v[52:55]
	v_mfma_f32_16x16x32_bf16 v[48:51], v[158:161], v[194:197], v[48:51]
	v_mfma_f32_16x16x32_bf16 v[28:31], v[166:169], v[190:193], v[28:31]
	v_mfma_f32_16x16x32_bf16 v[24:27], v[174:177], v[190:193], v[24:27]
	v_mfma_f32_16x16x32_bf16 v[28:31], v[170:173], v[194:197], v[28:31]
	v_mfma_f32_16x16x32_bf16 v[24:27], v[178:181], v[194:197], v[24:27]
	s_cmp_eq_u32 s12, 0
	s_cbranch_scc1 .Lp10_skA1
	v_mfma_f32_16x16x32_bf16 v[36:39], v[146:149], v[198:201], v[36:39]
	v_mfma_f32_16x16x32_bf16 v[32:35], v[154:157], v[198:201], v[32:35]
	v_mfma_f32_16x16x32_bf16 v[36:39], v[150:153], v[202:205], v[36:39]
	v_mfma_f32_16x16x32_bf16 v[32:35], v[158:161], v[202:205], v[32:35]
	v_mfma_f32_16x16x32_bf16 v[12:15], v[166:169], v[198:201], v[12:15]
	v_mfma_f32_16x16x32_bf16 v[8:11], v[174:177], v[198:201], v[8:11]
	v_mfma_f32_16x16x32_bf16 v[12:15], v[170:173], v[202:205], v[12:15]
	v_mfma_f32_16x16x32_bf16 v[8:11], v[178:181], v[202:205], v[8:11]
.Lp10_skA1:
	s_setprio 0
	s_barrier
	s_add_i32 s71, 0, 0x18000
	s_add_i32 s72, 0, 0x1c000
	v_add_u32_e32 v158, s71, v141
	v_add_u32_e32 v165, s72, v141
	ds_read_b128 v[146:149], v158
	ds_read_b128 v[150:153], v158 offset:1024
	ds_read_b128 v[154:157], v158 offset:2048
	ds_read_b128 v[158:161], v158 offset:3072
	ds_read_b128 v[166:169], v165
	ds_read_b128 v[170:173], v165 offset:1024
	ds_read_b128 v[174:177], v165 offset:2048
	ds_read_b128 v[178:181], v165 offset:3072
	s_add_u32 s46, s46, 0x6e000
	s_addc_u32 s47, s47, 0
	v_lshl_add_u64 v[220:221], s[46:47], 0, v[128:129]
	ds_read_b128 v[182:185], v145 offset:32768
	ds_read_b128 v[186:189], v145 offset:33792
	ds_read_b128 v[190:193], v145 offset:34816
	ds_read_b128 v[194:197], v145 offset:35840
	ds_read_b128 v[198:201], v145 offset:36864
	ds_read_b128 v[202:205], v145 offset:37888
	v_lshl_add_u64 v[220:221], s[46:47], 0, v[130:131]
	s_mov_b32 m0, s53
	s_nop 0
	global_load_lds_dwordx4 v[220:221], off
	s_waitcnt vmcnt(6)
	s_waitcnt lgkmcnt(0)
	s_barrier
	s_setprio 1
	s_waitcnt lgkmcnt(0)
	v_mfma_f32_16x16x32_bf16 v[124:127], v[146:149], v[182:185], v[124:127]
	v_mfma_f32_16x16x32_bf16 v[120:123], v[154:157], v[182:185], v[120:123]
	v_mfma_f32_16x16x32_bf16 v[124:127], v[150:153], v[186:189], v[124:127]
	v_mfma_f32_16x16x32_bf16 v[120:123], v[158:161], v[186:189], v[120:123]
	v_mfma_f32_16x16x32_bf16 v[108:111], v[166:169], v[182:185], v[108:111]
	v_mfma_f32_16x16x32_bf16 v[104:107], v[174:177], v[182:185], v[104:107]
	v_mfma_f32_16x16x32_bf16 v[108:111], v[170:173], v[186:189], v[108:111]
	v_mfma_f32_16x16x32_bf16 v[104:107], v[178:181], v[186:189], v[104:107]
	v_mfma_f32_16x16x32_bf16 v[116:119], v[146:149], v[190:193], v[116:119]
	v_mfma_f32_16x16x32_bf16 v[112:115], v[154:157], v[190:193], v[112:115]
	v_mfma_f32_16x16x32_bf16 v[116:119], v[150:153], v[194:197], v[116:119]
	v_mfma_f32_16x16x32_bf16 v[112:115], v[158:161], v[194:197], v[112:115]
	v_mfma_f32_16x16x32_bf16 v[92:95], v[166:169], v[190:193], v[92:95]
	v_mfma_f32_16x16x32_bf16 v[88:91], v[174:177], v[190:193], v[88:91]
	v_mfma_f32_16x16x32_bf16 v[92:95], v[170:173], v[194:197], v[92:95]
	v_mfma_f32_16x16x32_bf16 v[88:91], v[178:181], v[194:197], v[88:91]
	s_cmp_eq_u32 s12, 0
	s_cbranch_scc1 .Lp10_skA2
	v_mfma_f32_16x16x32_bf16 v[100:103], v[146:149], v[198:201], v[100:103]
	v_mfma_f32_16x16x32_bf16 v[96:99], v[154:157], v[198:201], v[96:99]
	v_mfma_f32_16x16x32_bf16 v[100:103], v[150:153], v[202:205], v[100:103]
	v_mfma_f32_16x16x32_bf16 v[96:99], v[158:161], v[202:205], v[96:99]
	v_mfma_f32_16x16x32_bf16 v[76:79], v[166:169], v[198:201], v[76:79]
	v_mfma_f32_16x16x32_bf16 v[72:75], v[174:177], v[198:201], v[72:75]
	v_mfma_f32_16x16x32_bf16 v[76:79], v[170:173], v[202:205], v[76:79]
	v_mfma_f32_16x16x32_bf16 v[72:75], v[178:181], v[202:205], v[72:75]
.Lp10_skA2:
	s_setprio 0
	s_barrier
	s_add_i32 s46, s71, s48
	v_lshl_add_u64 v[162:163], v[162:163], 0, s[10:11]
	s_mov_b32 m0, s46
	ds_read_b128 v[182:185], v145 offset:49152
	ds_read_b128 v[186:189], v145 offset:50176
	ds_read_b128 v[190:193], v145 offset:51200
	ds_read_b128 v[194:197], v145 offset:52224
	ds_read_b128 v[198:201], v145 offset:53248
	ds_read_b128 v[202:205], v145 offset:54272
	global_load_lds_dwordx4 v[162:163], off
	s_add_i32 m0, s46, 0x2000
	s_add_u32 s44, s44, 0xb0080
	v_lshl_add_u64 v[162:163], v[214:215], 0, s[10:11]
	s_addc_u32 s45, s45, 0
	s_add_i32 s46, s72, s48
	global_load_lds_dwordx4 v[162:163], off
	v_lshl_add_u64 v[162:163], s[44:45], 0, v[128:129]
	s_mov_b32 m0, s46
	s_nop 0
	global_load_lds_dwordx4 v[162:163], off
	v_lshl_add_u64 v[162:163], s[44:45], 0, v[130:131]
	s_add_i32 m0, s46, 0x2000
	s_nop 0
	global_load_lds_dwordx4 v[162:163], off
	v_lshl_add_u64 v[162:163], v[216:217], 0, s[10:11]
	s_nop 0
	v_lshl_add_u64 v[162:163], v[218:219], 0, s[10:11]
	s_mov_b32 m0, s57
	s_nop 0
	global_load_lds_dwordx4 v[162:163], off
	s_waitcnt vmcnt(6)
	s_waitcnt lgkmcnt(0)
	s_barrier
	s_setprio 1
	s_waitcnt lgkmcnt(0)
	v_mfma_f32_16x16x32_bf16 v[60:63], v[146:149], v[182:185], v[60:63]
	v_mfma_f32_16x16x32_bf16 v[56:59], v[154:157], v[182:185], v[56:59]
	v_mfma_f32_16x16x32_bf16 v[60:63], v[150:153], v[186:189], v[60:63]
	v_mfma_f32_16x16x32_bf16 v[56:59], v[158:161], v[186:189], v[56:59]
	v_mfma_f32_16x16x32_bf16 v[44:47], v[166:169], v[182:185], v[44:47]
	v_mfma_f32_16x16x32_bf16 v[40:43], v[174:177], v[182:185], v[40:43]
	v_mfma_f32_16x16x32_bf16 v[44:47], v[170:173], v[186:189], v[44:47]
	v_mfma_f32_16x16x32_bf16 v[40:43], v[178:181], v[186:189], v[40:43]
	v_mfma_f32_16x16x32_bf16 v[52:55], v[146:149], v[190:193], v[52:55]
	v_mfma_f32_16x16x32_bf16 v[48:51], v[154:157], v[190:193], v[48:51]
	v_mfma_f32_16x16x32_bf16 v[52:55], v[150:153], v[194:197], v[52:55]
	v_mfma_f32_16x16x32_bf16 v[48:51], v[158:161], v[194:197], v[48:51]
	v_mfma_f32_16x16x32_bf16 v[28:31], v[166:169], v[190:193], v[28:31]
	v_mfma_f32_16x16x32_bf16 v[24:27], v[174:177], v[190:193], v[24:27]
	v_mfma_f32_16x16x32_bf16 v[28:31], v[170:173], v[194:197], v[28:31]
	v_mfma_f32_16x16x32_bf16 v[24:27], v[178:181], v[194:197], v[24:27]
	s_cmp_eq_u32 s12, 0
	s_cbranch_scc1 .Lp10_skA3
	v_mfma_f32_16x16x32_bf16 v[36:39], v[146:149], v[198:201], v[36:39]
	v_mfma_f32_16x16x32_bf16 v[32:35], v[154:157], v[198:201], v[32:35]
	v_mfma_f32_16x16x32_bf16 v[36:39], v[150:153], v[202:205], v[36:39]
	v_mfma_f32_16x16x32_bf16 v[32:35], v[158:161], v[202:205], v[32:35]
	v_mfma_f32_16x16x32_bf16 v[12:15], v[166:169], v[198:201], v[12:15]
	v_mfma_f32_16x16x32_bf16 v[8:11], v[174:177], v[198:201], v[8:11]
	v_mfma_f32_16x16x32_bf16 v[12:15], v[170:173], v[202:205], v[12:15]
	v_mfma_f32_16x16x32_bf16 v[8:11], v[178:181], v[202:205], v[8:11]

.LBB0_1061:
	s_mul_i32 s98, s66, 0xa0
	v_lshl_or_b32 v216, s67, 8, v142
	v_add_u32_e32 v214, s98, v140
	v_ashrrev_i32_e32 v217, 31, v216
	v_ashrrev_i32_e32 v215, 31, v214
	v_lshlrev_b64 v[216:217], 1, v[216:217]
	v_lshlrev_b64 v[218:219], 11, v[214:215]
	v_lshl_add_u64 v[218:219], s[42:43], 0, v[218:219]
	v_lshl_add_u64 v[218:219], v[218:219], 0, v[216:217]
	v_cvt_pk_bf16_f32 v166, v124, v125
	v_cvt_pk_bf16_f32 v167, v126, v127
	v_cvt_pk_bf16_f32 v168, v120, v121
	v_cvt_pk_bf16_f32 v169, v122, v123
	global_store_dwordx4 v[218:219], v[166:169], off
	v_cvt_pk_bf16_f32 v170, v108, v109
	v_cvt_pk_bf16_f32 v171, v110, v111
	v_cvt_pk_bf16_f32 v172, v104, v105
	v_cvt_pk_bf16_f32 v173, v106, v107
	global_store_dwordx4 v[218:219], v[170:173], off offset:256
	v_mov_b32_e32 v148, 0x8000
	v_mov_b32_e32 v149, 0
	v_lshl_add_u64 v[148:149], v[218:219], 0, v[148:149]
	v_cvt_pk_bf16_f32 v174, v116, v117
	v_cvt_pk_bf16_f32 v175, v118, v119
	v_cvt_pk_bf16_f32 v176, v112, v113
	v_cvt_pk_bf16_f32 v177, v114, v115
	global_store_dwordx4 v[148:149], v[174:177], off
	v_cvt_pk_bf16_f32 v178, v92, v93
	v_cvt_pk_bf16_f32 v179, v94, v95
	v_cvt_pk_bf16_f32 v180, v88, v89
	v_cvt_pk_bf16_f32 v181, v90, v91
	global_store_dwordx4 v[148:149], v[178:181], off offset:256
	v_mov_b32_e32 v150, 0x28000
	v_mov_b32_e32 v151, 0
	v_lshl_add_u64 v[150:151], v[218:219], 0, v[150:151]
	v_cvt_pk_bf16_f32 v182, v60, v61
	v_cvt_pk_bf16_f32 v183, v62, v63
	v_cvt_pk_bf16_f32 v184, v56, v57
	v_cvt_pk_bf16_f32 v185, v58, v59
	global_store_dwordx4 v[150:151], v[182:185], off
	v_cvt_pk_bf16_f32 v186, v44, v45
	v_cvt_pk_bf16_f32 v187, v46, v47
	v_cvt_pk_bf16_f32 v188, v40, v41
	v_cvt_pk_bf16_f32 v189, v42, v43
	global_store_dwordx4 v[150:151], v[186:189], off offset:256
	v_mov_b32_e32 v152, 0x30000
	v_mov_b32_e32 v153, 0
	v_lshl_add_u64 v[152:153], v[218:219], 0, v[152:153]
	v_cvt_pk_bf16_f32 v190, v52, v53
	v_cvt_pk_bf16_f32 v191, v54, v55
	v_cvt_pk_bf16_f32 v192, v48, v49
	v_cvt_pk_bf16_f32 v193, v50, v51
	global_store_dwordx4 v[152:153], v[190:193], off
	v_cvt_pk_bf16_f32 v194, v28, v29
	v_cvt_pk_bf16_f32 v195, v30, v31
	v_cvt_pk_bf16_f32 v196, v24, v25
	v_cvt_pk_bf16_f32 v197, v26, v27
	global_store_dwordx4 v[152:153], v[194:197], off offset:256
	s_cmp_eq_u32 s12, 0
	s_cbranch_scc1 .Lp10_epi_done
	v_mov_b32_e32 v154, 0x10000
	v_mov_b32_e32 v155, 0
	v_lshl_add_u64 v[154:155], v[218:219], 0, v[154:155]
	v_cvt_pk_bf16_f32 v198, v100, v101
	v_cvt_pk_bf16_f32 v199, v102, v103
	v_cvt_pk_bf16_f32 v200, v96, v97
	v_cvt_pk_bf16_f32 v201, v98, v99
	global_store_dwordx4 v[154:155], v[198:201], off
	v_cvt_pk_bf16_f32 v202, v76, v77
	v_cvt_pk_bf16_f32 v203, v78, v79
	v_cvt_pk_bf16_f32 v204, v72, v73
	v_cvt_pk_bf16_f32 v205, v74, v75
	global_store_dwordx4 v[154:155], v[202:205], off offset:256
	v_mov_b32_e32 v156, 0x38000
	v_mov_b32_e32 v157, 0
	v_lshl_add_u64 v[156:157], v[218:219], 0, v[156:157]
	v_cvt_pk_bf16_f32 v206, v36, v37
	v_cvt_pk_bf16_f32 v207, v38, v39
	v_cvt_pk_bf16_f32 v208, v32, v33
	v_cvt_pk_bf16_f32 v209, v34, v35
	global_store_dwordx4 v[156:157], v[206:209], off
	v_cvt_pk_bf16_f32 v210, v12, v13
	v_cvt_pk_bf16_f32 v211, v14, v15
	v_cvt_pk_bf16_f32 v212, v8, v9
	v_cvt_pk_bf16_f32 v213, v10, v11
	global_store_dwordx4 v[156:157], v[210:213], off offset:256

	.amdhsa_kernel _Z6fwd_mk4Args
		.amdhsa_group_segment_fixed_size 0
		.amdhsa_private_segment_fixed_size 0
		.amdhsa_kernarg_size 440
		.amdhsa_user_sgpr_count 2
		.amdhsa_user_sgpr_dispatch_ptr 0
		.amdhsa_user_sgpr_queue_ptr 0
		.amdhsa_user_sgpr_kernarg_segment_ptr 1
		.amdhsa_user_sgpr_dispatch_id 0
		.amdhsa_user_sgpr_kernarg_preload_length 0
		.amdhsa_user_sgpr_kernarg_preload_offset 0
		.amdhsa_user_sgpr_private_segment_size 0
		.amdhsa_uses_dynamic_stack 0
		.amdhsa_enable_private_segment 0
		.amdhsa_system_sgpr_workgroup_id_x 1
		.amdhsa_system_sgpr_workgroup_id_y 0
		.amdhsa_system_sgpr_workgroup_id_z 0
		.amdhsa_system_sgpr_workgroup_info 0
		.amdhsa_system_vgpr_workitem_id 0
		.amdhsa_next_free_vgpr 245
		.amdhsa_next_free_sgpr 99
		.amdhsa_accum_offset 248
		.amdhsa_reserve_vcc 1
		.amdhsa_float_round_mode_32 0
		.amdhsa_float_round_mode_16_64 0
		.amdhsa_float_denorm_mode_32 3
		.amdhsa_float_denorm_mode_16_64 3
		.amdhsa_dx10_clamp 1
		.amdhsa_ieee_mode 1
		.amdhsa_fp16_overflow 0
		.amdhsa_tg_split 0
		.amdhsa_exception_fp_ieee_invalid_op 0
		.amdhsa_exception_fp_denorm_src 0
		.amdhsa_exception_fp_ieee_div_zero 0
		.amdhsa_exception_fp_ieee_overflow 0
		.amdhsa_exception_fp_ieee_underflow 0
		.amdhsa_exception_fp_ieee_inexact 0
		.amdhsa_exception_int_div_zero 0
	.end_amdhsa_kernel

amdhsa.kernels:
  - .agpr_count:     0
    .args:
      - .offset:         0
        .size:           184
        .value_kind:     by_value
      - .offset:         184
        .size:           4
        .value_kind:     hidden_block_count_x
      - .offset:         188
        .size:           4
        .value_kind:     hidden_block_count_y
      - .offset:         192
        .size:           4
        .value_kind:     hidden_block_count_z
      - .offset:         196
        .size:           2
        .value_kind:     hidden_group_size_x
      - .offset:         198
        .size:           2
        .value_kind:     hidden_group_size_y
      - .offset:         200
        .size:           2
        .value_kind:     hidden_group_size_z
      - .offset:         202
        .size:           2
        .value_kind:     hidden_remainder_x
      - .offset:         204
        .size:           2
        .value_kind:     hidden_remainder_y
      - .offset:         206
        .size:           2
        .value_kind:     hidden_remainder_z
      - .offset:         224
        .size:           8
        .value_kind:     hidden_global_offset_x
      - .offset:         232
        .size:           8
        .value_kind:     hidden_global_offset_y
      - .offset:         240
        .size:           8
        .value_kind:     hidden_global_offset_z
      - .offset:         248
        .size:           2
        .value_kind:     hidden_grid_dims
      - .offset:         304
        .size:           4
        .value_kind:     hidden_dynamic_lds_size
    .group_segment_fixed_size: 0
    .kernarg_segment_align: 8
    .kernarg_segment_size: 440
    .language:       OpenCL C
    .language_version:
      - 2
      - 0
    .max_flat_workgroup_size: 512
    .name:           _Z6fwd_mk4Args
    .private_segment_fixed_size: 0
    .sgpr_count:     105
    .sgpr_spill_count: 10
    .symbol:         _Z6fwd_mk4Args.kd
    .uniform_work_group_size: 1
    .uses_dynamic_stack: false
    .vgpr_count:     245
    .vgpr_spill_count: 0
    .wavefront_size: 64
